# phase-6 epilogue rewritten: f16 row stores widened from 16x dwordx2 to 8x dwordx4 per lane via v_permlane16_swap pairs (same bytes/addresses)
# speedup vs baseline: 1.0136x; 1.0085x over previous
; DI int BIDX() { int b = blockIdx.x; asm volatile("" : "+s"(b)); return b; }
; DI int tile_groups(int MT, int NT) { return (MT >> 6) * ((NT + 7) >> 3) * 512; }
; DI void load_rstd(float (&rs)[4], const float* ssq, int row0, int lr) {
; #pragma unroll
;   for (int mt = 0; mt < 4; ++mt) {
;     const float4* q = (const float4*)(ssq + (size_t)(row0 + mt * 16 + lr) * 16);
;     const float4 a = q[0], b = q[1], c = q[2], d = q[3];
;     const float s = ((a.x + a.y) + (a.z + a.w)) + ((b.x + b.y) + (b.z + b.w)) + ((c.x + c.y) + (c.z + c.w)) + ((d.x + d.y) + (d.z + d.w));
;     rs[mt] = rsqrtf(s * (1.0f / 1024.0f) + EPS);
;   }
; }
; template <int VAR> DI void phase_up(const Params& P, int l, char* smem) {
;     ...
;   for (int vb = BIDX(); vb < tile_groups(128, 32); vb += gridDim.x) {
;     int tm, tn; if (!tile_of(vb, 128, 32, tm, tn)) continue;
;     const int m0 = tm * 128, n0 = tn * 128;
;     const int row0 = m0 + wm * 64, col0 = n0 + wn * 64;
;     f32x4 acc[4][4]; zero_acc(acc);
;     float rs[4]; load_rstd(rs, ssq, row0, lr);
.LBB0_1313:
	s_ashr_i32 s4, s2, 9
	s_lshr_b32 s1, s4, 30
	s_add_i32 s1, s4, s1
	s_ashr_i32 s5, s1, 2
	s_lshl_b32 s1, s5, 6
	s_and_b32 s6, s12, 56
	s_lshl_b32 s5, s5, 5
	s_lshl_b32 s4, s4, 3
	s_or_b32 s1, s1, s6
	s_bfe_u32 s6, s2, 0x30003
	s_sub_i32 s4, s4, s5
	s_bfe_u32 s5, s2, 0x30006
	s_or_b32 s1, s1, s6
	s_or_b32 s4, s4, s5
	s_cmpk_lt_i32 s1, 0x80
	s_cselect_b64 s[6:7], -1, 0
	s_cmp_lt_i32 s4, 32
	s_cselect_b64 s[8:9], -1, 0
	s_and_b64 s[6:7], s[6:7], s[8:9]
	s_andn2_b64 vcc, exec, s[6:7]
	s_cbranch_vccnz .LBB0_1312
	s_lshl_b32 s8, s1, 7
	v_add_u32_e32 v102, s8, v125
	v_ashrrev_i32_e32 v103, 31, v102
	v_readlane_b32 s14, v254, 41
	v_lshlrev_b64 v[0:1], 6, v[102:103]
	v_readlane_b32 s15, v254, 42
	v_or_b32_e32 v98, 16, v102
	v_ashrrev_i32_e32 v99, 31, v98
	v_lshl_add_u64 v[12:13], s[14:15], 0, v[0:1]
	global_load_dwordx4 v[0:3], v[12:13], off offset:32
	global_load_dwordx4 v[4:7], v[12:13], off offset:16
	global_load_dwordx4 v[8:11], v[12:13], off
	s_nop 0
	global_load_dwordx4 v[12:15], v[12:13], off offset:48
	s_lshl_b32 s6, s4, 7
	s_mov_b32 s4, 0x358637bd
	s_mov_b32 s16, 0x3a800000
	s_mov_b32 s1, 0x800000
	v_or_b32_e32 v106, 32, v102
	v_ashrrev_i32_e32 v107, 31, v106
	v_or_b32_e32 v104, 48, v102
	v_ashrrev_i32_e32 v105, 31, v104
	s_ashr_i32 s9, s8, 31
	s_waitcnt vmcnt(7)
	v_mov_b32_e32 v72, v148
	v_or_b32_e32 v100, s6, v124
	s_waitcnt vmcnt(2)
	v_mov_b32_e32 v18, v5
	s_waitcnt vmcnt(1)
	v_mov_b32_e32 v16, v9
	v_mov_b32_e32 v17, v10
	v_mov_b32_e32 v19, v6
	v_mov_b32_e32 v9, v11
	v_mov_b32_e32 v5, v7
	v_mov_b32_e32 v6, v1
	v_pk_add_f32 v[8:9], v[16:17], v[8:9]
	v_pk_add_f32 v[4:5], v[18:19], v[4:5]
	v_pk_add_f32 v[0:1], v[0:1], v[6:7]
	v_mov_b32_e32 v6, v3
	v_pk_add_f32 v[8:9], v[8:9], v[8:9] op_sel:[0,1] op_sel_hi:[1,0]
	v_pk_add_f32 v[4:5], v[4:5], v[4:5] op_sel:[0,1] op_sel_hi:[1,0]
	v_pk_add_f32 v[2:3], v[2:3], v[6:7]
	s_waitcnt vmcnt(0)
	v_mov_b32_e32 v9, v12
	v_mov_b32_e32 v5, v13
	v_mov_b32_e32 v1, v14
	v_mov_b32_e32 v3, v15
	v_pk_add_f32 v[4:5], v[8:9], v[4:5]
	v_pk_add_f32 v[0:1], v[0:1], v[2:3]
	s_nop 0
	v_pk_add_f32 v[16:17], v[4:5], v[0:1]
	v_lshlrev_b64 v[0:1], 6, v[98:99]
	v_lshl_add_u64 v[12:13], s[14:15], 0, v[0:1]
	global_load_dwordx4 v[0:3], v[12:13], off offset:32
	global_load_dwordx4 v[4:7], v[12:13], off offset:16
	global_load_dwordx4 v[8:11], v[12:13], off
	s_nop 0
	global_load_dwordx4 v[12:15], v[12:13], off offset:48
	s_waitcnt vmcnt(2)
	v_mov_b32_e32 v20, v5
	s_waitcnt vmcnt(1)
	v_mov_b32_e32 v18, v9
	v_mov_b32_e32 v19, v10
	v_mov_b32_e32 v21, v6
	v_mov_b32_e32 v9, v11
	v_mov_b32_e32 v5, v7
	v_mov_b32_e32 v6, v1
	v_pk_add_f32 v[8:9], v[18:19], v[8:9]
	v_pk_add_f32 v[4:5], v[20:21], v[4:5]
	v_pk_add_f32 v[0:1], v[0:1], v[6:7]
	v_mov_b32_e32 v6, v3
	v_pk_add_f32 v[8:9], v[8:9], v[8:9] op_sel:[0,1] op_sel_hi:[1,0]
	v_pk_add_f32 v[4:5], v[4:5], v[4:5] op_sel:[0,1] op_sel_hi:[1,0]
	v_pk_add_f32 v[2:3], v[2:3], v[6:7]
	s_waitcnt vmcnt(0)
	v_mov_b32_e32 v9, v12
	v_mov_b32_e32 v5, v13
	v_mov_b32_e32 v1, v14
	v_mov_b32_e32 v3, v15
	v_pk_add_f32 v[4:5], v[8:9], v[4:5]
	v_pk_add_f32 v[0:1], v[0:1], v[2:3]
	v_mov_b32_e32 v3, v16
	v_pk_add_f32 v[0:1], v[4:5], v[0:1]
	s_nop 0
	v_mov_b32_e32 v2, v0
	v_mov_b32_e32 v16, v1
	v_pk_add_f32 v[2:3], v[2:3], v[16:17]
	v_mov_b64_e32 v[0:1], s[4:5]
	v_pk_fma_f32 v[2:3], v[2:3], s[16:17], v[0:1] op_sel_hi:[1,0,0]
	s_nop 0
	v_mul_f32_e32 v4, 0x4b800000, v3
	v_cmp_gt_f32_e64 s[4:5], s1, v3
	v_cmp_gt_f32_e32 vcc, s1, v2
	s_nop 0
	v_cndmask_b32_e64 v3, v3, v4, s[4:5]
	v_rsq_f32_e32 v3, v3
	s_nop 0
	v_mul_f32_e32 v4, 0x45800000, v3
	v_cndmask_b32_e64 v128, v3, v4, s[4:5]
	v_mul_f32_e32 v3, 0x4b800000, v2
	v_cndmask_b32_e32 v2, v2, v3, vcc
	v_rsq_f32_e32 v2, v2
	s_nop 0
	v_mul_f32_e32 v3, 0x45800000, v2
	v_cndmask_b32_e32 v126, v2, v3, vcc
	v_lshlrev_b64 v[2:3], 6, v[106:107]
	v_lshl_add_u64 v[14:15], s[14:15], 0, v[2:3]
	global_load_dwordx4 v[2:5], v[14:15], off offset:32
	global_load_dwordx4 v[6:9], v[14:15], off offset:16
	global_load_dwordx4 v[10:13], v[14:15], off
	s_nop 0
	global_load_dwordx4 v[14:17], v[14:15], off offset:48
	s_waitcnt vmcnt(2)
	v_mov_b32_e32 v20, v7
	s_waitcnt vmcnt(1)
	v_mov_b32_e32 v18, v11
	v_mov_b32_e32 v19, v12
	v_mov_b32_e32 v21, v8
	v_mov_b32_e32 v11, v13
	v_mov_b32_e32 v7, v9
	v_mov_b32_e32 v8, v3
	v_pk_add_f32 v[10:11], v[18:19], v[10:11]
	v_pk_add_f32 v[6:7], v[20:21], v[6:7]
	v_pk_add_f32 v[2:3], v[2:3], v[8:9]
	v_mov_b32_e32 v8, v5
	v_pk_add_f32 v[10:11], v[10:11], v[10:11] op_sel:[0,1] op_sel_hi:[1,0]
	v_pk_add_f32 v[6:7], v[6:7], v[6:7] op_sel:[0,1] op_sel_hi:[1,0]
	v_pk_add_f32 v[4:5], v[4:5], v[8:9]
	s_waitcnt vmcnt(0)
	v_mov_b32_e32 v11, v14
	v_mov_b32_e32 v7, v15
	v_mov_b32_e32 v3, v16
	v_mov_b32_e32 v5, v17
	v_pk_add_f32 v[6:7], v[10:11], v[6:7]
	v_pk_add_f32 v[2:3], v[2:3], v[4:5]
	s_nop 0
	v_pk_add_f32 v[18:19], v[6:7], v[2:3]
	v_lshlrev_b64 v[2:3], 6, v[104:105]
	v_lshl_add_u64 v[14:15], s[14:15], 0, v[2:3]
	global_load_dwordx4 v[2:5], v[14:15], off offset:32
	global_load_dwordx4 v[6:9], v[14:15], off offset:16
	global_load_dwordx4 v[10:13], v[14:15], off
	s_nop 0
	global_load_dwordx4 v[14:17], v[14:15], off offset:48
	s_waitcnt vmcnt(2)
	v_mov_b32_e32 v22, v7
	s_waitcnt vmcnt(1)
	v_mov_b32_e32 v20, v11
	v_mov_b32_e32 v21, v12
	v_mov_b32_e32 v23, v8
	v_mov_b32_e32 v11, v13
	v_mov_b32_e32 v7, v9
	v_mov_b32_e32 v8, v3
	v_pk_add_f32 v[10:11], v[20:21], v[10:11]
	v_pk_add_f32 v[6:7], v[22:23], v[6:7]
	v_pk_add_f32 v[2:3], v[2:3], v[8:9]
	v_mov_b32_e32 v8, v5
	v_pk_add_f32 v[10:11], v[10:11], v[10:11] op_sel:[0,1] op_sel_hi:[1,0]
	v_pk_add_f32 v[6:7], v[6:7], v[6:7] op_sel:[0,1] op_sel_hi:[1,0]
	v_pk_add_f32 v[4:5], v[4:5], v[8:9]
	s_waitcnt vmcnt(0)
; DI int TIDX() { int t = threadIdx.x; asm volatile("" : "+v"(t)); return t; }
; #define GL_LOAD(s_, kt_) if (VAR != 1) { a##s_##0 = GL_A(0, kt_); a##s_##1 = GL_A(1, kt_); a##s_##2 = GL_A(2, kt_); a##s_##3 = GL_A(3, kt_); b##s_##0 = GL_B(0, kt_); b##s_##1 = GL_B(1, kt_); b##s_##2 = GL_B(2, kt_); b##s_##3 = GL_B(3, kt_); }
; #define LDS_STORE(s_, buf_) if (VAR != 2) { LDS_ST1(sA, 0, buf_, a##s_##0) LDS_ST1(sA, 1, buf_, a##s_##1) LDS_ST1(sA, 2, buf_, a##s_##2) LDS_ST1(sA, 3, buf_, a##s_##3) LDS_ST1(sB, 0, buf_, b##s_##0) LDS_ST1(sB, 1, buf_, b##s_##1) LDS_ST1(sB, 2, buf_, b##s_##2) LDS_ST1(sB, 3, buf_, b##s_##3) }
;   const int tid = TIDX(), lane = tid & 63, wid = tid >> 6, wm = wid >> 1, wn = wid & 1, lr = lane & 15, g = lane >> 4;
;   char* sA = smem; char* sB = smem + 2 * LTILE;
;   uint4 a00 = {}, a01 = {}, a02 = {}, a03 = {}, b00 = {}, b01 = {}, b02 = {}, b03 = {}, a10 = {}, a11 = {}, a12 = {}, a13 = {}, b10 = {}, b11 = {}, b12 = {}, b13 = {};
;   constexpr int nk = NK;
;   const int sw0 = (g ^ ((lr >> 1) & 7)) << 4, sw1 = sw0 ^ 64;
;   const int r0 = tid >> 3, kc = tid & 7, kcs = kc ^ ((r0 >> 1) & 7);
;     ...
;   GL_LOAD(0, 0)
;   GL_LOAD(1, 1)
;   LDS_STORE(0, 0)
;   if (VAR != 4) __syncthreads();
	v_mov_b32_e32 v11, v14
	v_mov_b32_e32 v7, v15
	v_mov_b32_e32 v3, v16
	v_mov_b32_e32 v5, v17
	v_pk_add_f32 v[6:7], v[10:11], v[6:7]
	v_pk_add_f32 v[2:3], v[2:3], v[4:5]
	v_mov_b32_e32 v5, v18
	v_pk_add_f32 v[2:3], v[6:7], v[2:3]
	v_ashrrev_i32_e32 v64, 3, v72
	v_mov_b32_e32 v4, v2
	v_mov_b32_e32 v18, v3
	v_pk_add_f32 v[2:3], v[4:5], v[18:19]
	v_ashrrev_i32_e32 v65, 31, v64
	v_pk_fma_f32 v[0:1], v[2:3], s[16:17], v[0:1] op_sel_hi:[1,0,0]
	v_and_b32_e32 v75, 48, v72
	v_mul_f32_e32 v2, 0x4b800000, v1
	v_cmp_gt_f32_e64 s[4:5], s1, v1
	v_cmp_gt_f32_e32 vcc, s1, v0
	v_lshlrev_b64 v[16:17], 11, v[64:65]
	v_cndmask_b32_e64 v1, v1, v2, s[4:5]
	v_rsq_f32_e32 v1, v1
	v_lshlrev_b32_e32 v65, 4, v72
	v_and_b32_e32 v150, 0x70, v65
	v_add_u32_e32 v66, 32, v64
	v_mul_f32_e32 v2, 0x45800000, v1
	v_cndmask_b32_e64 v129, v1, v2, s[4:5]
	v_mul_f32_e32 v1, 0x4b800000, v0
	v_cndmask_b32_e32 v0, v0, v1, vcc
	v_rsq_f32_e32 v0, v0
	s_lshl_b64 s[4:5], s[8:9], 11
	v_readlane_b32 s8, v254, 43
	v_readlane_b32 s9, v254, 44
	v_mul_f32_e32 v1, 0x45800000, v0
	s_add_u32 s4, s8, s4
	v_cndmask_b32_e32 v127, v0, v1, vcc
	s_addc_u32 s5, s9, s5
	v_lshlrev_b32_e32 v0, 3, v72
	s_ashr_i32 s7, s6, 31
	v_and_b32_e32 v74, 0x70, v0
	v_bitop3_b32 v134, v0, v75, s23 bitop3:0x6c
	v_lshl_add_u64 v[0:1], s[4:5], 0, v[16:17]
	v_add_u32_e32 v68, 64, v64
	v_add_u32_e32 v70, 0x60, v64
	s_lshl_b64 s[6:7], s[6:7], 11
	v_lshl_add_u64 v[108:109], v[0:1], 0, v[150:151]
	v_ashrrev_i32_e32 v67, 31, v66
	v_ashrrev_i32_e32 v69, 31, v68
	v_ashrrev_i32_e32 v71, 31, v70
	s_add_u32 s6, s10, s6
	v_lshlrev_b64 v[20:21], 11, v[66:67]
	v_lshlrev_b64 v[24:25], 11, v[68:69]
	v_lshlrev_b64 v[28:29], 11, v[70:71]
	s_addc_u32 s7, s11, s7
	v_lshl_add_u64 v[4:5], s[4:5], 0, v[20:21]
	v_lshl_add_u64 v[8:9], s[4:5], 0, v[24:25]
	v_lshl_add_u64 v[12:13], s[4:5], 0, v[28:29]
	v_lshl_add_u64 v[110:111], v[4:5], 0, v[150:151]
	v_lshl_add_u64 v[112:113], v[8:9], 0, v[150:151]
	v_lshl_add_u64 v[114:115], v[12:13], 0, v[150:151]
	v_lshl_add_u64 v[16:17], s[6:7], 0, v[16:17]
	v_lshl_add_u64 v[116:117], v[16:17], 0, v[150:151]
	v_lshl_add_u64 v[20:21], s[6:7], 0, v[20:21]
	v_lshl_add_u64 v[118:119], v[20:21], 0, v[150:151]
	v_lshl_add_u64 v[24:25], s[6:7], 0, v[24:25]
	v_lshl_add_u64 v[120:121], v[24:25], 0, v[150:151]
	v_lshl_add_u64 v[28:29], s[6:7], 0, v[28:29]
	v_lshl_add_u64 v[122:123], v[28:29], 0, v[150:151]
	v_bitop3_b32 v65, v65, s23, v72 bitop3:0x48
	v_lshl_or_b32 v101, v64, 7, v65
	v_and_b32_e32 v73, 15, v72
	v_lshl_or_b32 v131, v66, 7, v65
	v_lshl_or_b32 v132, v68, 7, v65
	v_lshl_or_b32 v130, v70, 7, v65
	v_xor_b32_e32 v135, 64, v134
	v_writelane_b32 v255, s60, 0
	v_writelane_b32 v255, s61, 1
	v_writelane_b32 v255, s62, 2
	v_writelane_b32 v255, s63, 3
	v_writelane_b32 v255, s64, 4
	v_writelane_b32 v255, s65, 5
	v_writelane_b32 v255, s66, 6
	v_writelane_b32 v255, s67, 7
	v_writelane_b32 v255, s68, 8
	v_writelane_b32 v255, s69, 9
	v_writelane_b32 v255, s70, 10
	v_writelane_b32 v255, s71, 11
	v_writelane_b32 v255, s72, 12
	v_writelane_b32 v255, s73, 13
	v_writelane_b32 v255, s74, 14
	v_writelane_b32 v255, s75, 15
	v_mov_b32_e32 v3, v101
	v_and_b32_e32 v3, 0xffffff80, v3
	s_nop 0
	v_readfirstlane_b32 s60, v3
	v_add_u32_e32 v3, 0x4000, v101
	v_and_b32_e32 v3, 0xffffff80, v3
	s_nop 0
	v_readfirstlane_b32 s61, v3
	v_add_u32_e32 v3, 0x8000, v101
	v_and_b32_e32 v3, 0xffffff80, v3
	s_nop 0
	v_readfirstlane_b32 s62, v3
	v_add_u32_e32 v3, 0xc000, v101
	v_and_b32_e32 v3, 0xffffff80, v3
	s_nop 0
	v_readfirstlane_b32 s63, v3
	v_mov_b32_e32 v3, v130
	v_and_b32_e32 v3, 0xffffff80, v3
	s_nop 0
	v_readfirstlane_b32 s64, v3
	v_add_u32_e32 v3, 0x4000, v130
	v_and_b32_e32 v3, 0xffffff80, v3
	s_nop 0
	v_readfirstlane_b32 s65, v3
	v_add_u32_e32 v3, 0x8000, v130
	v_and_b32_e32 v3, 0xffffff80, v3
	s_nop 0
	v_readfirstlane_b32 s66, v3
	v_add_u32_e32 v3, 0xc000, v130
	v_and_b32_e32 v3, 0xffffff80, v3
	s_nop 0
	v_readfirstlane_b32 s67, v3
	v_mov_b32_e32 v3, v131
	v_and_b32_e32 v3, 0xffffff80, v3
	s_nop 0
	v_readfirstlane_b32 s68, v3
	v_add_u32_e32 v3, 0x4000, v131
	v_and_b32_e32 v3, 0xffffff80, v3
	s_nop 0
	v_readfirstlane_b32 s69, v3
	v_add_u32_e32 v3, 0x8000, v131
	v_and_b32_e32 v3, 0xffffff80, v3
	s_nop 0
	v_readfirstlane_b32 s70, v3
	v_add_u32_e32 v3, 0xc000, v131
	v_and_b32_e32 v3, 0xffffff80, v3
	s_nop 0
	v_readfirstlane_b32 s71, v3
	v_mov_b32_e32 v3, v132
	v_and_b32_e32 v3, 0xffffff80, v3
	s_nop 0
	v_readfirstlane_b32 s72, v3
	v_add_u32_e32 v3, 0x4000, v132
	v_and_b32_e32 v3, 0xffffff80, v3
	s_nop 0
	v_readfirstlane_b32 s73, v3
	v_add_u32_e32 v3, 0x8000, v132
	v_and_b32_e32 v3, 0xffffff80, v3
	s_nop 0
	v_readfirstlane_b32 s74, v3
	v_add_u32_e32 v3, 0xc000, v132
	v_and_b32_e32 v3, 0xffffff80, v3
	s_nop 0
	v_readfirstlane_b32 s75, v3
	v_and_b32_e32 v30, 7, v148
	v_bfe_u32 v31, v148, 4, 3
	v_xor_b32_e32 v31, v31, v30
	v_sub_u32_e32 v31, v31, v30
	v_lshlrev_b32_e32 v30, 4, v31
	v_ashrrev_i32_e32 v31, 31, v30
	v_lshl_add_u64 v[0:1], v[108:109], 0, v[30:31]
	s_mov_b32 m0, s60
	s_nop 0
	global_load_lds_dwordx4 v[0:1], off
	v_lshrrev_b32_e32 v0, 1, v72
	v_and_or_b32 v0, v0, s24, v73
	v_lshlrev_b32_e32 v137, 7, v0
	v_lshlrev_b32_e32 v0, 7, v72
	v_and_b32_e32 v146, 0x2780, v0
	v_bitop3_b32 v133, v137, v74, v75 bitop3:0xf6
	v_or_b32_e32 v136, v146, v134
	v_bitop3_b32 v134, v137, v134, 64 bitop3:0xf6
	v_or_b32_e32 v135, v146, v135
	v_lshl_add_u64 v[4:5], v[110:111], 0, v[30:31]
	s_mov_b32 m0, s68
	s_nop 0
	global_load_lds_dwordx4 v[4:5], off
	v_lshl_add_u64 v[8:9], v[112:113], 0, v[30:31]
	s_mov_b32 m0, s72
	s_nop 0
	global_load_lds_dwordx4 v[8:9], off
	v_lshl_add_u64 v[12:13], v[114:115], 0, v[30:31]
	s_mov_b32 m0, s64
	s_nop 0
	global_load_lds_dwordx4 v[12:13], off
	v_lshl_add_u64 v[16:17], v[116:117], 0, v[30:31]
	s_mov_b32 m0, s62
	s_nop 0
	global_load_lds_dwordx4 v[16:17], off
	v_lshl_add_u64 v[20:21], v[118:119], 0, v[30:31]
	s_mov_b32 m0, s70
	s_nop 0
	global_load_lds_dwordx4 v[20:21], off
	v_lshl_add_u64 v[24:25], v[120:121], 0, v[30:31]
	s_mov_b32 m0, s74
	s_nop 0
	global_load_lds_dwordx4 v[24:25], off
	v_lshl_add_u64 v[28:29], v[122:123], 0, v[30:31]
	s_mov_b32 m0, s66
	s_nop 0
	global_load_lds_dwordx4 v[28:29], off
	s_waitcnt lgkmcnt(0)
	s_waitcnt vmcnt(0)
	s_barrier
; #define GL_LOAD(s_, kt_) if (VAR != 1) { a##s_##0 = GL_A(0, kt_); a##s_##1 = GL_A(1, kt_); a##s_##2 = GL_A(2, kt_); a##s_##3 = GL_A(3, kt_); b##s_##0 = GL_B(0, kt_); b##s_##1 = GL_B(1, kt_); b##s_##2 = GL_B(2, kt_); b##s_##3 = GL_B(3, kt_); }
; #define LDS_STORE(s_, buf_) if (VAR != 2) { LDS_ST1(sA, 0, buf_, a##s_##0) LDS_ST1(sA, 1, buf_, a##s_##1) LDS_ST1(sA, 2, buf_, a##s_##2) LDS_ST1(sA, 3, buf_, a##s_##3) LDS_ST1(sB, 0, buf_, b##s_##0) LDS_ST1(sB, 1, buf_, b##s_##1) LDS_ST1(sB, 2, buf_, b##s_##2) LDS_ST1(sB, 3, buf_, b##s_##3) }
;     ...
;   GL_LOAD(0, 0)
;   GL_LOAD(1, 1)
;   LDS_STORE(0, 0)
;   if (VAR != 4) __syncthreads();
; #pragma unroll
;   for (int kt = 0; kt < nk; kt += 2) {
;     if (kt + 2 < nk) { GL_LOAD(0, kt + 2) }
;     MMA_TILE(0)
;     LDS_STORE(1, 1)
;     if (VAR != 4) __syncthreads();
;     if (kt + 3 < nk) { GL_LOAD(1, kt + 3) }
;     MMA_TILE(1)
;     if (kt + 2 < nk) { LDS_STORE(0, 0) }
;     if (VAR != 4) __syncthreads();
;   }
	s_setprio 1
	ds_read_b128 v[64:67], v133
	ds_read_b128 v[68:71], v136 offset:32768
	s_waitcnt lgkmcnt(0)
	v_mfma_f32_16x16x32_f16 v[138:141], v[68:71], v[64:67], 0
	ds_read_b128 v[72:75], v133 offset:2048
	ds_read_b128 v[76:79], v136 offset:34816
	s_waitcnt lgkmcnt(1)
	v_mfma_f32_16x16x32_f16 v[158:161], v[68:71], v[72:75], 0
	ds_read_b128 v[80:83], v133 offset:4096
	ds_read_b128 v[84:87], v136 offset:36864
	s_waitcnt lgkmcnt(2)
	v_mfma_f32_16x16x32_f16 v[142:145], v[76:79], v[64:67], 0
	ds_read_b128 v[88:91], v133 offset:6144
	ds_read_b128 v[92:95], v136 offset:38912
	v_mfma_f32_16x16x32_f16 v[162:165], v[76:79], v[72:75], 0
	ds_read_b128 v[202:205], v135 offset:32768
	ds_read_b128 v[206:209], v134 offset:2048
	s_waitcnt lgkmcnt(5)
	v_mfma_f32_16x16x32_f16 v[190:193], v[68:71], v[80:83], 0
	ds_read_b128 v[210:213], v135 offset:34816
	ds_read_b128 v[220:223], v134 offset:4096
	s_waitcnt lgkmcnt(5)
	v_mfma_f32_16x16x32_f16 v[68:71], v[68:71], v[88:91], 0
	ds_read_b128 v[224:227], v135 offset:36864
	v_mfma_f32_16x16x32_f16 v[194:197], v[76:79], v[80:83], 0
	ds_read_b128 v[228:231], v134 offset:6144
	v_mfma_f32_16x16x32_f16 v[76:79], v[76:79], v[88:91], 0
	ds_read_b128 v[232:235], v135 offset:38912
	v_mfma_f32_16x16x32_f16 v[154:157], v[84:87], v[64:67], 0
	v_mfma_f32_16x16x32_f16 v[166:169], v[84:87], v[72:75], 0
	s_waitcnt lgkmcnt(7)
	v_mfma_f32_16x16x32_f16 v[64:67], v[92:95], v[64:67], 0
	v_mfma_f32_16x16x32_f16 v[72:75], v[92:95], v[72:75], 0
	v_mfma_f32_16x16x32_f16 v[198:201], v[84:87], v[80:83], 0
	v_and_b32_e32 v62, 7, v148
	v_bfe_u32 v63, v148, 4, 3
	v_xor_b32_e32 v63, v63, v62
	v_sub_u32_e32 v63, v63, v62
	v_lshlrev_b32_e32 v62, 4, v63
	v_add_u32_e32 v62, 0x80, v62
	v_ashrrev_i32_e32 v63, 31, v62
	v_mfma_f32_16x16x32_f16 v[84:87], v[84:87], v[88:91], 0
	v_lshl_add_u64 v[32:33], v[108:109], 0, v[62:63]
	s_mov_b32 m0, s61
	s_nop 0
	global_load_lds_dwordx4 v[32:33], off
	v_lshl_add_u64 v[36:37], v[110:111], 0, v[62:63]
	s_mov_b32 m0, s69
	s_nop 0
	global_load_lds_dwordx4 v[36:37], off
	v_mfma_f32_16x16x32_f16 v[80:83], v[92:95], v[80:83], 0
	v_lshl_add_u64 v[40:41], v[112:113], 0, v[62:63]
	s_mov_b32 m0, s73
	s_nop 0
	global_load_lds_dwordx4 v[40:41], off
	v_lshl_add_u64 v[44:45], v[114:115], 0, v[62:63]
	s_mov_b32 m0, s65
	s_nop 0
	global_load_lds_dwordx4 v[44:45], off
	v_mfma_f32_16x16x32_f16 v[88:91], v[92:95], v[88:91], 0
	ds_read_b128 v[92:95], v134
	v_lshl_add_u64 v[48:49], v[116:117], 0, v[62:63]
	s_mov_b32 m0, s63
	s_nop 0
	global_load_lds_dwordx4 v[48:49], off
	v_lshl_add_u64 v[52:53], v[118:119], 0, v[62:63]
	s_mov_b32 m0, s71
	s_nop 0
	global_load_lds_dwordx4 v[52:53], off
	v_lshl_add_u64 v[56:57], v[120:121], 0, v[62:63]
	s_mov_b32 m0, s75
	s_nop 0
	global_load_lds_dwordx4 v[56:57], off
	v_lshl_add_u64 v[60:61], v[122:123], 0, v[62:63]
	s_mov_b32 m0, s67
	s_nop 0
	global_load_lds_dwordx4 v[60:61], off
	s_waitcnt vmcnt(0) lgkmcnt(0)
	s_barrier
	v_mfma_f32_16x16x32_f16 v[138:141], v[202:205], v[92:95], v[138:141]
	v_mfma_f32_16x16x32_f16 v[142:145], v[210:213], v[92:95], v[142:145]
	v_mfma_f32_16x16x32_f16 v[154:157], v[224:227], v[92:95], v[154:157]
	v_mfma_f32_16x16x32_f16 v[64:67], v[232:235], v[92:95], v[64:67]
	v_mfma_f32_16x16x32_f16 v[92:95], v[202:205], v[206:209], v[158:161]
	v_mfma_f32_16x16x32_f16 v[158:161], v[210:213], v[206:209], v[162:165]
	v_mfma_f32_16x16x32_f16 v[162:165], v[224:227], v[206:209], v[166:169]
	v_mfma_f32_16x16x32_f16 v[166:169], v[202:205], v[220:223], v[190:193]
	v_mfma_f32_16x16x32_f16 v[68:71], v[202:205], v[228:231], v[68:71]
	ds_read_b128 v[202:205], v136 offset:49152
	v_mfma_f32_16x16x32_f16 v[190:193], v[210:213], v[220:223], v[194:197]
	v_mfma_f32_16x16x32_f16 v[76:79], v[210:213], v[228:231], v[76:79]
	ds_read_b128 v[210:213], v136 offset:51200
	v_and_b32_e32 v30, 7, v148
	v_bfe_u32 v31, v148, 4, 3
	v_xor_b32_e32 v31, v31, v30
	v_sub_u32_e32 v31, v31, v30
	v_lshlrev_b32_e32 v30, 4, v31
	v_add_u32_e32 v30, 0x100, v30
	v_ashrrev_i32_e32 v31, 31, v30
	v_mfma_f32_16x16x32_f16 v[72:75], v[232:235], v[206:209], v[72:75]
	ds_read_b128 v[206:209], v133 offset:18432
	v_mfma_f32_16x16x32_f16 v[194:197], v[224:227], v[220:223], v[198:201]
	s_nop 2
	ds_read_b128 v[198:201], v133 offset:16384
	v_mfma_f32_16x16x32_f16 v[84:87], v[224:227], v[228:231], v[84:87]
	ds_read_b128 v[224:227], v136 offset:53248
	v_mfma_f32_16x16x32_f16 v[80:83], v[232:235], v[220:223], v[80:83]
	ds_read_b128 v[220:223], v133 offset:20480
	v_mfma_f32_16x16x32_f16 v[88:91], v[232:235], v[228:231], v[88:91]
	ds_read_b128 v[228:231], v133 offset:22528
	s_waitcnt lgkmcnt(3)
	v_mfma_f32_16x16x32_f16 v[138:141], v[202:205], v[198:201], v[138:141]
	ds_read_b128 v[232:235], v136 offset:55296
	v_mfma_f32_16x16x32_f16 v[92:95], v[202:205], v[206:209], v[92:95]
	v_lshl_add_u64 v[0:1], v[108:109], 0, v[30:31]
	s_mov_b32 m0, s60
	s_nop 0
	global_load_lds_dwordx4 v[0:1], off
	v_mfma_f32_16x16x32_f16 v[142:145], v[210:213], v[198:201], v[142:145]
	v_lshl_add_u64 v[4:5], v[110:111], 0, v[30:31]
	s_mov_b32 m0, s68
	s_nop 0
	global_load_lds_dwordx4 v[4:5], off
	v_mfma_f32_16x16x32_f16 v[158:161], v[210:213], v[206:209], v[158:161]
	v_lshl_add_u64 v[8:9], v[112:113], 0, v[30:31]
	s_mov_b32 m0, s72
	s_nop 0
	global_load_lds_dwordx4 v[8:9], off
	s_waitcnt lgkmcnt(2)
	v_mfma_f32_16x16x32_f16 v[166:169], v[202:205], v[220:223], v[166:169]
	v_lshl_add_u64 v[12:13], v[114:115], 0, v[30:31]
	s_mov_b32 m0, s64
	s_nop 0
	global_load_lds_dwordx4 v[12:13], off
	s_waitcnt lgkmcnt(1)
; #define GL_LOAD(s_, kt_) if (VAR != 1) { a##s_##0 = GL_A(0, kt_); a##s_##1 = GL_A(1, kt_); a##s_##2 = GL_A(2, kt_); a##s_##3 = GL_A(3, kt_); b##s_##0 = GL_B(0, kt_); b##s_##1 = GL_B(1, kt_); b##s_##2 = GL_B(2, kt_); b##s_##3 = GL_B(3, kt_); }
; #define LDS_STORE(s_, buf_) if (VAR != 2) { LDS_ST1(sA, 0, buf_, a##s_##0) LDS_ST1(sA, 1, buf_, a##s_##1) LDS_ST1(sA, 2, buf_, a##s_##2) LDS_ST1(sA, 3, buf_, a##s_##3) LDS_ST1(sB, 0, buf_, b##s_##0) LDS_ST1(sB, 1, buf_, b##s_##1) LDS_ST1(sB, 2, buf_, b##s_##2) LDS_ST1(sB, 3, buf_, b##s_##3) }
;     ...
;   GL_LOAD(0, 0)
;   GL_LOAD(1, 1)
;   LDS_STORE(0, 0)
;   if (VAR != 4) __syncthreads();
; #pragma unroll
;   for (int kt = 0; kt < nk; kt += 2) {
;     if (kt + 2 < nk) { GL_LOAD(0, kt + 2) }
;     MMA_TILE(0)
;     LDS_STORE(1, 1)
;     if (VAR != 4) __syncthreads();
;     if (kt + 3 < nk) { GL_LOAD(1, kt + 3) }
;     MMA_TILE(1)
;     if (kt + 2 < nk) { LDS_STORE(0, 0) }
;     if (VAR != 4) __syncthreads();
;   }
	v_mfma_f32_16x16x32_f16 v[68:71], v[202:205], v[228:231], v[68:71]
	ds_read_b128 v[202:205], v135 offset:49152
	v_mfma_f32_16x16x32_f16 v[190:193], v[210:213], v[220:223], v[190:193]
	v_lshl_add_u64 v[16:17], v[116:117], 0, v[30:31]
	s_mov_b32 m0, s62
	s_nop 0
	global_load_lds_dwordx4 v[16:17], off
	v_mfma_f32_16x16x32_f16 v[76:79], v[210:213], v[228:231], v[76:79]
	ds_read_b128 v[210:213], v135 offset:51200
	v_mfma_f32_16x16x32_f16 v[154:157], v[224:227], v[198:201], v[154:157]
	v_lshl_add_u64 v[20:21], v[118:119], 0, v[30:31]
	s_mov_b32 m0, s70
	s_nop 0
	global_load_lds_dwordx4 v[20:21], off
	v_mfma_f32_16x16x32_f16 v[162:165], v[224:227], v[206:209], v[162:165]
	v_lshl_add_u64 v[24:25], v[120:121], 0, v[30:31]
	s_mov_b32 m0, s74
	s_nop 0
	global_load_lds_dwordx4 v[24:25], off
	s_waitcnt lgkmcnt(2)
	v_mfma_f32_16x16x32_f16 v[64:67], v[232:235], v[198:201], v[64:67]
	ds_read_b128 v[198:201], v134 offset:16384
	v_mfma_f32_16x16x32_f16 v[72:75], v[232:235], v[206:209], v[72:75]
	ds_read_b128 v[206:209], v134 offset:18432
	v_mfma_f32_16x16x32_f16 v[194:197], v[224:227], v[220:223], v[194:197]
	v_lshl_add_u64 v[28:29], v[122:123], 0, v[30:31]
	s_mov_b32 m0, s66
	s_nop 0
	global_load_lds_dwordx4 v[28:29], off
	v_mfma_f32_16x16x32_f16 v[84:87], v[224:227], v[228:231], v[84:87]
	ds_read_b128 v[224:227], v135 offset:53248
	v_mfma_f32_16x16x32_f16 v[80:83], v[232:235], v[220:223], v[80:83]
	ds_read_b128 v[220:223], v134 offset:20480
	v_mfma_f32_16x16x32_f16 v[88:91], v[232:235], v[228:231], v[88:91]
	ds_read_b128 v[228:231], v134 offset:22528
	ds_read_b128 v[232:235], v135 offset:55296
	s_waitcnt vmcnt(0) lgkmcnt(0)
	s_barrier
	v_mfma_f32_16x16x32_f16 v[138:141], v[202:205], v[198:201], v[138:141]
	v_mfma_f32_16x16x32_f16 v[92:95], v[202:205], v[206:209], v[92:95]
	v_mfma_f32_16x16x32_f16 v[142:145], v[210:213], v[198:201], v[142:145]
	v_mfma_f32_16x16x32_f16 v[158:161], v[210:213], v[206:209], v[158:161]
	v_mfma_f32_16x16x32_f16 v[166:169], v[202:205], v[220:223], v[166:169]
	v_mfma_f32_16x16x32_f16 v[68:71], v[202:205], v[228:231], v[68:71]
	ds_read_b128 v[202:205], v136 offset:32768
	v_mfma_f32_16x16x32_f16 v[190:193], v[210:213], v[220:223], v[190:193]
	v_mfma_f32_16x16x32_f16 v[76:79], v[210:213], v[228:231], v[76:79]
	ds_read_b128 v[210:213], v136 offset:34816
	v_mfma_f32_16x16x32_f16 v[154:157], v[224:227], v[198:201], v[154:157]
	v_mfma_f32_16x16x32_f16 v[162:165], v[224:227], v[206:209], v[162:165]
	v_mfma_f32_16x16x32_f16 v[64:67], v[232:235], v[198:201], v[64:67]
	ds_read_b128 v[198:201], v133
	v_mfma_f32_16x16x32_f16 v[72:75], v[232:235], v[206:209], v[72:75]
	ds_read_b128 v[206:209], v133 offset:2048
	v_mfma_f32_16x16x32_f16 v[194:197], v[224:227], v[220:223], v[194:197]
	v_and_b32_e32 v62, 7, v148
	v_bfe_u32 v63, v148, 4, 3
	v_xor_b32_e32 v63, v63, v62
	v_sub_u32_e32 v63, v63, v62
	v_lshlrev_b32_e32 v62, 4, v63
	v_add_u32_e32 v62, 0x180, v62
	v_ashrrev_i32_e32 v63, 31, v62
	v_mfma_f32_16x16x32_f16 v[84:87], v[224:227], v[228:231], v[84:87]
	ds_read_b128 v[224:227], v136 offset:36864
	v_mfma_f32_16x16x32_f16 v[80:83], v[232:235], v[220:223], v[80:83]
	ds_read_b128 v[220:223], v133 offset:4096
	v_mfma_f32_16x16x32_f16 v[88:91], v[232:235], v[228:231], v[88:91]
	ds_read_b128 v[228:231], v133 offset:6144
	s_waitcnt lgkmcnt(4)
	v_mfma_f32_16x16x32_f16 v[138:141], v[202:205], v[198:201], v[138:141]
	ds_read_b128 v[232:235], v136 offset:38912
	s_waitcnt lgkmcnt(4)
	v_mfma_f32_16x16x32_f16 v[92:95], v[202:205], v[206:209], v[92:95]
	v_lshl_add_u64 v[32:33], v[108:109], 0, v[62:63]
	s_mov_b32 m0, s61
	s_nop 0
	global_load_lds_dwordx4 v[32:33], off
	v_mfma_f32_16x16x32_f16 v[142:145], v[210:213], v[198:201], v[142:145]
	v_lshl_add_u64 v[36:37], v[110:111], 0, v[62:63]
	s_mov_b32 m0, s69
	s_nop 0
	global_load_lds_dwordx4 v[36:37], off
	v_mfma_f32_16x16x32_f16 v[158:161], v[210:213], v[206:209], v[158:161]
	v_lshl_add_u64 v[40:41], v[112:113], 0, v[62:63]
	s_mov_b32 m0, s73
	s_nop 0
	global_load_lds_dwordx4 v[40:41], off
	s_waitcnt lgkmcnt(2)
	v_mfma_f32_16x16x32_f16 v[166:169], v[202:205], v[220:223], v[166:169]
	v_lshl_add_u64 v[44:45], v[114:115], 0, v[62:63]
	s_mov_b32 m0, s65
	s_nop 0
	global_load_lds_dwordx4 v[44:45], off
	s_waitcnt lgkmcnt(1)
	v_mfma_f32_16x16x32_f16 v[68:71], v[202:205], v[228:231], v[68:71]
	ds_read_b128 v[202:205], v135 offset:32768
	v_mfma_f32_16x16x32_f16 v[190:193], v[210:213], v[220:223], v[190:193]
	v_lshl_add_u64 v[48:49], v[116:117], 0, v[62:63]
	s_mov_b32 m0, s63
	s_nop 0
	global_load_lds_dwordx4 v[48:49], off
	v_mfma_f32_16x16x32_f16 v[76:79], v[210:213], v[228:231], v[76:79]
	ds_read_b128 v[210:213], v135 offset:34816
	v_mfma_f32_16x16x32_f16 v[154:157], v[224:227], v[198:201], v[154:157]
	v_lshl_add_u64 v[52:53], v[118:119], 0, v[62:63]
	s_mov_b32 m0, s71
	s_nop 0
	global_load_lds_dwordx4 v[52:53], off
	v_mfma_f32_16x16x32_f16 v[162:165], v[224:227], v[206:209], v[162:165]
	v_lshl_add_u64 v[56:57], v[120:121], 0, v[62:63]
	s_mov_b32 m0, s75
	s_nop 0
	global_load_lds_dwordx4 v[56:57], off
	s_waitcnt lgkmcnt(2)
	v_mfma_f32_16x16x32_f16 v[64:67], v[232:235], v[198:201], v[64:67]
	ds_read_b128 v[198:201], v134
	v_mfma_f32_16x16x32_f16 v[72:75], v[232:235], v[206:209], v[72:75]
	ds_read_b128 v[206:209], v134 offset:2048
	v_mfma_f32_16x16x32_f16 v[194:197], v[224:227], v[220:223], v[194:197]
	v_lshl_add_u64 v[60:61], v[122:123], 0, v[62:63]
	s_mov_b32 m0, s67
	s_nop 0
	global_load_lds_dwordx4 v[60:61], off
	v_mfma_f32_16x16x32_f16 v[84:87], v[224:227], v[228:231], v[84:87]
	ds_read_b128 v[224:227], v135 offset:36864
	v_mfma_f32_16x16x32_f16 v[80:83], v[232:235], v[220:223], v[80:83]
	ds_read_b128 v[220:223], v134 offset:4096
	v_mfma_f32_16x16x32_f16 v[88:91], v[232:235], v[228:231], v[88:91]
	ds_read_b128 v[228:231], v134 offset:6144
	ds_read_b128 v[232:235], v135 offset:38912
	s_waitcnt vmcnt(0) lgkmcnt(0)
	s_barrier
; #define GL_LOAD(s_, kt_) if (VAR != 1) { a##s_##0 = GL_A(0, kt_); a##s_##1 = GL_A(1, kt_); a##s_##2 = GL_A(2, kt_); a##s_##3 = GL_A(3, kt_); b##s_##0 = GL_B(0, kt_); b##s_##1 = GL_B(1, kt_); b##s_##2 = GL_B(2, kt_); b##s_##3 = GL_B(3, kt_); }
; #define LDS_STORE(s_, buf_) if (VAR != 2) { LDS_ST1(sA, 0, buf_, a##s_##0) LDS_ST1(sA, 1, buf_, a##s_##1) LDS_ST1(sA, 2, buf_, a##s_##2) LDS_ST1(sA, 3, buf_, a##s_##3) LDS_ST1(sB, 0, buf_, b##s_##0) LDS_ST1(sB, 1, buf_, b##s_##1) LDS_ST1(sB, 2, buf_, b##s_##2) LDS_ST1(sB, 3, buf_, b##s_##3) }
;     ...
;   GL_LOAD(0, 0)
;   GL_LOAD(1, 1)
;   LDS_STORE(0, 0)
;   if (VAR != 4) __syncthreads();
; #pragma unroll
;   for (int kt = 0; kt < nk; kt += 2) {
;     if (kt + 2 < nk) { GL_LOAD(0, kt + 2) }
;     MMA_TILE(0)
;     LDS_STORE(1, 1)
;     if (VAR != 4) __syncthreads();
;     if (kt + 3 < nk) { GL_LOAD(1, kt + 3) }
;     MMA_TILE(1)
;     if (kt + 2 < nk) { LDS_STORE(0, 0) }
;     if (VAR != 4) __syncthreads();
;   }
	v_mfma_f32_16x16x32_f16 v[138:141], v[202:205], v[198:201], v[138:141]
	v_mfma_f32_16x16x32_f16 v[92:95], v[202:205], v[206:209], v[92:95]
	v_mfma_f32_16x16x32_f16 v[142:145], v[210:213], v[198:201], v[142:145]
	v_mfma_f32_16x16x32_f16 v[158:161], v[210:213], v[206:209], v[158:161]
	v_mfma_f32_16x16x32_f16 v[166:169], v[202:205], v[220:223], v[166:169]
	v_mfma_f32_16x16x32_f16 v[68:71], v[202:205], v[228:231], v[68:71]
	ds_read_b128 v[202:205], v136 offset:49152
	v_mfma_f32_16x16x32_f16 v[190:193], v[210:213], v[220:223], v[190:193]
	v_mfma_f32_16x16x32_f16 v[76:79], v[210:213], v[228:231], v[76:79]
	ds_read_b128 v[210:213], v136 offset:51200
	v_mfma_f32_16x16x32_f16 v[154:157], v[224:227], v[198:201], v[154:157]
	v_mfma_f32_16x16x32_f16 v[162:165], v[224:227], v[206:209], v[162:165]
	v_mfma_f32_16x16x32_f16 v[64:67], v[232:235], v[198:201], v[64:67]
	ds_read_b128 v[198:201], v133 offset:16384
	v_mfma_f32_16x16x32_f16 v[72:75], v[232:235], v[206:209], v[72:75]
	ds_read_b128 v[206:209], v133 offset:18432
	v_mfma_f32_16x16x32_f16 v[194:197], v[224:227], v[220:223], v[194:197]
	v_and_b32_e32 v30, 7, v148
	v_bfe_u32 v31, v148, 4, 3
	v_xor_b32_e32 v31, v31, v30
	v_sub_u32_e32 v31, v31, v30
	v_lshlrev_b32_e32 v30, 4, v31
	v_add_u32_e32 v30, 0x200, v30
	v_ashrrev_i32_e32 v31, 31, v30
	v_mfma_f32_16x16x32_f16 v[84:87], v[224:227], v[228:231], v[84:87]
	ds_read_b128 v[224:227], v136 offset:53248
	v_mfma_f32_16x16x32_f16 v[80:83], v[232:235], v[220:223], v[80:83]
	ds_read_b128 v[220:223], v133 offset:20480
	v_mfma_f32_16x16x32_f16 v[88:91], v[232:235], v[228:231], v[88:91]
	ds_read_b128 v[228:231], v133 offset:22528
	s_waitcnt lgkmcnt(4)
	v_mfma_f32_16x16x32_f16 v[138:141], v[202:205], v[198:201], v[138:141]
	ds_read_b128 v[232:235], v136 offset:55296
	s_waitcnt lgkmcnt(4)
	v_mfma_f32_16x16x32_f16 v[92:95], v[202:205], v[206:209], v[92:95]
	v_lshl_add_u64 v[0:1], v[108:109], 0, v[30:31]
	s_mov_b32 m0, s60
	s_nop 0
	global_load_lds_dwordx4 v[0:1], off
	v_mfma_f32_16x16x32_f16 v[142:145], v[210:213], v[198:201], v[142:145]
	v_lshl_add_u64 v[4:5], v[110:111], 0, v[30:31]
	s_mov_b32 m0, s68
	s_nop 0
	global_load_lds_dwordx4 v[4:5], off
	v_mfma_f32_16x16x32_f16 v[158:161], v[210:213], v[206:209], v[158:161]
	v_lshl_add_u64 v[8:9], v[112:113], 0, v[30:31]
	s_mov_b32 m0, s72
	s_nop 0
	global_load_lds_dwordx4 v[8:9], off
	s_waitcnt lgkmcnt(2)
	v_mfma_f32_16x16x32_f16 v[166:169], v[202:205], v[220:223], v[166:169]
	v_lshl_add_u64 v[12:13], v[114:115], 0, v[30:31]
	s_mov_b32 m0, s64
	s_nop 0
	global_load_lds_dwordx4 v[12:13], off
	s_waitcnt lgkmcnt(1)
	v_mfma_f32_16x16x32_f16 v[68:71], v[202:205], v[228:231], v[68:71]
	ds_read_b128 v[202:205], v135 offset:49152
	v_mfma_f32_16x16x32_f16 v[190:193], v[210:213], v[220:223], v[190:193]
	v_lshl_add_u64 v[16:17], v[116:117], 0, v[30:31]
	s_mov_b32 m0, s62
	s_nop 0
	global_load_lds_dwordx4 v[16:17], off
	v_mfma_f32_16x16x32_f16 v[76:79], v[210:213], v[228:231], v[76:79]
	ds_read_b128 v[210:213], v135 offset:51200
	v_mfma_f32_16x16x32_f16 v[154:157], v[224:227], v[198:201], v[154:157]
	v_lshl_add_u64 v[20:21], v[118:119], 0, v[30:31]
	s_mov_b32 m0, s70
	s_nop 0
	global_load_lds_dwordx4 v[20:21], off
	v_mfma_f32_16x16x32_f16 v[162:165], v[224:227], v[206:209], v[162:165]
	v_lshl_add_u64 v[24:25], v[120:121], 0, v[30:31]
	s_mov_b32 m0, s74
	s_nop 0
	global_load_lds_dwordx4 v[24:25], off
	s_waitcnt lgkmcnt(2)
	v_mfma_f32_16x16x32_f16 v[64:67], v[232:235], v[198:201], v[64:67]
	ds_read_b128 v[198:201], v134 offset:16384
	v_mfma_f32_16x16x32_f16 v[72:75], v[232:235], v[206:209], v[72:75]
	ds_read_b128 v[206:209], v134 offset:18432
	v_mfma_f32_16x16x32_f16 v[194:197], v[224:227], v[220:223], v[194:197]
	v_lshl_add_u64 v[28:29], v[122:123], 0, v[30:31]
	s_mov_b32 m0, s66
	s_nop 0
	global_load_lds_dwordx4 v[28:29], off
	v_mfma_f32_16x16x32_f16 v[84:87], v[224:227], v[228:231], v[84:87]
	ds_read_b128 v[224:227], v135 offset:53248
	v_mfma_f32_16x16x32_f16 v[80:83], v[232:235], v[220:223], v[80:83]
	ds_read_b128 v[220:223], v134 offset:20480
	v_mfma_f32_16x16x32_f16 v[88:91], v[232:235], v[228:231], v[88:91]
	ds_read_b128 v[228:231], v134 offset:22528
	ds_read_b128 v[232:235], v135 offset:55296
	s_waitcnt vmcnt(0) lgkmcnt(0)
	s_barrier
	v_mfma_f32_16x16x32_f16 v[138:141], v[202:205], v[198:201], v[138:141]
	v_mfma_f32_16x16x32_f16 v[92:95], v[202:205], v[206:209], v[92:95]
	v_mfma_f32_16x16x32_f16 v[142:145], v[210:213], v[198:201], v[142:145]
	v_mfma_f32_16x16x32_f16 v[158:161], v[210:213], v[206:209], v[158:161]
	v_mfma_f32_16x16x32_f16 v[166:169], v[202:205], v[220:223], v[166:169]
	v_mfma_f32_16x16x32_f16 v[68:71], v[202:205], v[228:231], v[68:71]
	ds_read_b128 v[202:205], v136 offset:32768
	v_mfma_f32_16x16x32_f16 v[190:193], v[210:213], v[220:223], v[190:193]
	v_mfma_f32_16x16x32_f16 v[76:79], v[210:213], v[228:231], v[76:79]
	ds_read_b128 v[210:213], v136 offset:34816
	v_mfma_f32_16x16x32_f16 v[154:157], v[224:227], v[198:201], v[154:157]
	v_mfma_f32_16x16x32_f16 v[162:165], v[224:227], v[206:209], v[162:165]
	v_mfma_f32_16x16x32_f16 v[64:67], v[232:235], v[198:201], v[64:67]
	ds_read_b128 v[198:201], v133
	v_mfma_f32_16x16x32_f16 v[72:75], v[232:235], v[206:209], v[72:75]
	ds_read_b128 v[206:209], v133 offset:2048
	v_mfma_f32_16x16x32_f16 v[194:197], v[224:227], v[220:223], v[194:197]
	v_and_b32_e32 v62, 7, v148
	v_bfe_u32 v63, v148, 4, 3
	v_xor_b32_e32 v63, v63, v62
	v_sub_u32_e32 v63, v63, v62
	v_lshlrev_b32_e32 v62, 4, v63
	v_add_u32_e32 v62, 0x280, v62
	v_ashrrev_i32_e32 v63, 31, v62
	v_mfma_f32_16x16x32_f16 v[84:87], v[224:227], v[228:231], v[84:87]
	ds_read_b128 v[224:227], v136 offset:36864
	v_mfma_f32_16x16x32_f16 v[80:83], v[232:235], v[220:223], v[80:83]
	ds_read_b128 v[220:223], v133 offset:4096
	v_mfma_f32_16x16x32_f16 v[88:91], v[232:235], v[228:231], v[88:91]
	ds_read_b128 v[228:231], v133 offset:6144
	s_waitcnt lgkmcnt(4)
; #define GL_LOAD(s_, kt_) if (VAR != 1) { a##s_##0 = GL_A(0, kt_); a##s_##1 = GL_A(1, kt_); a##s_##2 = GL_A(2, kt_); a##s_##3 = GL_A(3, kt_); b##s_##0 = GL_B(0, kt_); b##s_##1 = GL_B(1, kt_); b##s_##2 = GL_B(2, kt_); b##s_##3 = GL_B(3, kt_); }
; #define LDS_STORE(s_, buf_) if (VAR != 2) { LDS_ST1(sA, 0, buf_, a##s_##0) LDS_ST1(sA, 1, buf_, a##s_##1) LDS_ST1(sA, 2, buf_, a##s_##2) LDS_ST1(sA, 3, buf_, a##s_##3) LDS_ST1(sB, 0, buf_, b##s_##0) LDS_ST1(sB, 1, buf_, b##s_##1) LDS_ST1(sB, 2, buf_, b##s_##2) LDS_ST1(sB, 3, buf_, b##s_##3) }
;     ...
;   GL_LOAD(0, 0)
;   GL_LOAD(1, 1)
;   LDS_STORE(0, 0)
;   if (VAR != 4) __syncthreads();
; #pragma unroll
;   for (int kt = 0; kt < nk; kt += 2) {
;     if (kt + 2 < nk) { GL_LOAD(0, kt + 2) }
;     MMA_TILE(0)
;     LDS_STORE(1, 1)
;     if (VAR != 4) __syncthreads();
;     if (kt + 3 < nk) { GL_LOAD(1, kt + 3) }
;     MMA_TILE(1)
;     if (kt + 2 < nk) { LDS_STORE(0, 0) }
;     if (VAR != 4) __syncthreads();
;   }
	v_mfma_f32_16x16x32_f16 v[138:141], v[202:205], v[198:201], v[138:141]
	ds_read_b128 v[232:235], v136 offset:38912
	s_waitcnt lgkmcnt(4)
	v_mfma_f32_16x16x32_f16 v[92:95], v[202:205], v[206:209], v[92:95]
	v_lshl_add_u64 v[32:33], v[108:109], 0, v[62:63]
	s_mov_b32 m0, s61
	s_nop 0
	global_load_lds_dwordx4 v[32:33], off
	v_mfma_f32_16x16x32_f16 v[142:145], v[210:213], v[198:201], v[142:145]
	v_lshl_add_u64 v[36:37], v[110:111], 0, v[62:63]
	s_mov_b32 m0, s69
	s_nop 0
	global_load_lds_dwordx4 v[36:37], off
	v_mfma_f32_16x16x32_f16 v[158:161], v[210:213], v[206:209], v[158:161]
	v_lshl_add_u64 v[40:41], v[112:113], 0, v[62:63]
	s_mov_b32 m0, s73
	s_nop 0
	global_load_lds_dwordx4 v[40:41], off
	s_waitcnt lgkmcnt(2)
	v_mfma_f32_16x16x32_f16 v[166:169], v[202:205], v[220:223], v[166:169]
	v_lshl_add_u64 v[44:45], v[114:115], 0, v[62:63]
	s_mov_b32 m0, s65
	s_nop 0
	global_load_lds_dwordx4 v[44:45], off
	s_waitcnt lgkmcnt(1)
	v_mfma_f32_16x16x32_f16 v[68:71], v[202:205], v[228:231], v[68:71]
	ds_read_b128 v[202:205], v135 offset:32768
	v_mfma_f32_16x16x32_f16 v[190:193], v[210:213], v[220:223], v[190:193]
	v_lshl_add_u64 v[48:49], v[116:117], 0, v[62:63]
	s_mov_b32 m0, s63
	s_nop 0
	global_load_lds_dwordx4 v[48:49], off
	v_mfma_f32_16x16x32_f16 v[76:79], v[210:213], v[228:231], v[76:79]
	ds_read_b128 v[210:213], v135 offset:34816
	v_mfma_f32_16x16x32_f16 v[154:157], v[224:227], v[198:201], v[154:157]
	v_lshl_add_u64 v[52:53], v[118:119], 0, v[62:63]
	s_mov_b32 m0, s71
	s_nop 0
	global_load_lds_dwordx4 v[52:53], off
	v_mfma_f32_16x16x32_f16 v[162:165], v[224:227], v[206:209], v[162:165]
	v_lshl_add_u64 v[56:57], v[120:121], 0, v[62:63]
	s_mov_b32 m0, s75
	s_nop 0
	global_load_lds_dwordx4 v[56:57], off
	s_waitcnt lgkmcnt(2)
	v_mfma_f32_16x16x32_f16 v[64:67], v[232:235], v[198:201], v[64:67]
	ds_read_b128 v[198:201], v134
	v_mfma_f32_16x16x32_f16 v[72:75], v[232:235], v[206:209], v[72:75]
	ds_read_b128 v[206:209], v134 offset:2048
	v_mfma_f32_16x16x32_f16 v[194:197], v[224:227], v[220:223], v[194:197]
	v_lshl_add_u64 v[60:61], v[122:123], 0, v[62:63]
	s_mov_b32 m0, s67
	s_nop 0
	global_load_lds_dwordx4 v[60:61], off
	v_mfma_f32_16x16x32_f16 v[84:87], v[224:227], v[228:231], v[84:87]
	ds_read_b128 v[224:227], v135 offset:36864
	v_mfma_f32_16x16x32_f16 v[80:83], v[232:235], v[220:223], v[80:83]
	ds_read_b128 v[220:223], v134 offset:4096
	v_mfma_f32_16x16x32_f16 v[88:91], v[232:235], v[228:231], v[88:91]
	ds_read_b128 v[228:231], v134 offset:6144
	ds_read_b128 v[232:235], v135 offset:38912
	s_waitcnt vmcnt(0) lgkmcnt(0)
	s_barrier
	v_mfma_f32_16x16x32_f16 v[138:141], v[202:205], v[198:201], v[138:141]
	v_mfma_f32_16x16x32_f16 v[92:95], v[202:205], v[206:209], v[92:95]
	v_mfma_f32_16x16x32_f16 v[142:145], v[210:213], v[198:201], v[142:145]
	v_mfma_f32_16x16x32_f16 v[158:161], v[210:213], v[206:209], v[158:161]
	v_mfma_f32_16x16x32_f16 v[166:169], v[202:205], v[220:223], v[166:169]
	v_mfma_f32_16x16x32_f16 v[68:71], v[202:205], v[228:231], v[68:71]
	ds_read_b128 v[202:205], v136 offset:49152
	v_mfma_f32_16x16x32_f16 v[190:193], v[210:213], v[220:223], v[190:193]
	v_mfma_f32_16x16x32_f16 v[76:79], v[210:213], v[228:231], v[76:79]
	ds_read_b128 v[210:213], v136 offset:51200
	v_mfma_f32_16x16x32_f16 v[154:157], v[224:227], v[198:201], v[154:157]
	v_mfma_f32_16x16x32_f16 v[162:165], v[224:227], v[206:209], v[162:165]
	v_mfma_f32_16x16x32_f16 v[64:67], v[232:235], v[198:201], v[64:67]
	ds_read_b128 v[198:201], v133 offset:16384
	v_mfma_f32_16x16x32_f16 v[72:75], v[232:235], v[206:209], v[72:75]
	ds_read_b128 v[206:209], v133 offset:18432
	v_mfma_f32_16x16x32_f16 v[194:197], v[224:227], v[220:223], v[194:197]
	v_and_b32_e32 v30, 7, v148
	v_bfe_u32 v31, v148, 4, 3
	v_xor_b32_e32 v31, v31, v30
	v_sub_u32_e32 v31, v31, v30
	v_lshlrev_b32_e32 v30, 4, v31
	v_add_u32_e32 v30, 0x300, v30
	v_ashrrev_i32_e32 v31, 31, v30
	v_mfma_f32_16x16x32_f16 v[84:87], v[224:227], v[228:231], v[84:87]
	ds_read_b128 v[224:227], v136 offset:53248
	v_mfma_f32_16x16x32_f16 v[80:83], v[232:235], v[220:223], v[80:83]
	ds_read_b128 v[220:223], v133 offset:20480
	v_mfma_f32_16x16x32_f16 v[88:91], v[232:235], v[228:231], v[88:91]
	ds_read_b128 v[228:231], v133 offset:22528
	s_waitcnt lgkmcnt(4)
	v_mfma_f32_16x16x32_f16 v[138:141], v[202:205], v[198:201], v[138:141]
	ds_read_b128 v[232:235], v136 offset:55296
	s_waitcnt lgkmcnt(4)
	v_mfma_f32_16x16x32_f16 v[92:95], v[202:205], v[206:209], v[92:95]
	v_lshl_add_u64 v[0:1], v[108:109], 0, v[30:31]
	s_mov_b32 m0, s60
	s_nop 0
	global_load_lds_dwordx4 v[0:1], off
	v_mfma_f32_16x16x32_f16 v[142:145], v[210:213], v[198:201], v[142:145]
	v_lshl_add_u64 v[4:5], v[110:111], 0, v[30:31]
	s_mov_b32 m0, s68
	s_nop 0
	global_load_lds_dwordx4 v[4:5], off
	v_mfma_f32_16x16x32_f16 v[158:161], v[210:213], v[206:209], v[158:161]
	v_lshl_add_u64 v[8:9], v[112:113], 0, v[30:31]
	s_mov_b32 m0, s72
	s_nop 0
	global_load_lds_dwordx4 v[8:9], off
	s_waitcnt lgkmcnt(2)
	v_mfma_f32_16x16x32_f16 v[166:169], v[202:205], v[220:223], v[166:169]
	v_lshl_add_u64 v[12:13], v[114:115], 0, v[30:31]
	s_mov_b32 m0, s64
	s_nop 0
	global_load_lds_dwordx4 v[12:13], off
	s_waitcnt lgkmcnt(1)
	v_mfma_f32_16x16x32_f16 v[68:71], v[202:205], v[228:231], v[68:71]
	ds_read_b128 v[202:205], v135 offset:49152
	v_mfma_f32_16x16x32_f16 v[190:193], v[210:213], v[220:223], v[190:193]
	v_lshl_add_u64 v[16:17], v[116:117], 0, v[30:31]
	s_mov_b32 m0, s62
	s_nop 0
	global_load_lds_dwordx4 v[16:17], off
	v_mfma_f32_16x16x32_f16 v[76:79], v[210:213], v[228:231], v[76:79]
	ds_read_b128 v[210:213], v135 offset:51200
	v_mfma_f32_16x16x32_f16 v[154:157], v[224:227], v[198:201], v[154:157]
	v_lshl_add_u64 v[20:21], v[118:119], 0, v[30:31]
	s_mov_b32 m0, s70
	s_nop 0
	global_load_lds_dwordx4 v[20:21], off
	v_mfma_f32_16x16x32_f16 v[162:165], v[224:227], v[206:209], v[162:165]
	v_lshl_add_u64 v[24:25], v[120:121], 0, v[30:31]
	s_mov_b32 m0, s74
	s_nop 0
	global_load_lds_dwordx4 v[24:25], off
	s_waitcnt lgkmcnt(2)
	v_mfma_f32_16x16x32_f16 v[64:67], v[232:235], v[198:201], v[64:67]
	ds_read_b128 v[198:201], v134 offset:16384
	v_mfma_f32_16x16x32_f16 v[72:75], v[232:235], v[206:209], v[72:75]
	ds_read_b128 v[206:209], v134 offset:18432
	v_mfma_f32_16x16x32_f16 v[194:197], v[224:227], v[220:223], v[194:197]
	v_lshl_add_u64 v[28:29], v[122:123], 0, v[30:31]
	s_mov_b32 m0, s66
	s_nop 0
	global_load_lds_dwordx4 v[28:29], off
	v_mfma_f32_16x16x32_f16 v[84:87], v[224:227], v[228:231], v[84:87]
	ds_read_b128 v[224:227], v135 offset:53248
	v_mfma_f32_16x16x32_f16 v[80:83], v[232:235], v[220:223], v[80:83]
	ds_read_b128 v[220:223], v134 offset:20480
	v_mfma_f32_16x16x32_f16 v[88:91], v[232:235], v[228:231], v[88:91]
	ds_read_b128 v[228:231], v134 offset:22528
	ds_read_b128 v[232:235], v135 offset:55296
	s_waitcnt vmcnt(0) lgkmcnt(0)
	s_barrier
; #define GL_LOAD(s_, kt_) if (VAR != 1) { a##s_##0 = GL_A(0, kt_); a##s_##1 = GL_A(1, kt_); a##s_##2 = GL_A(2, kt_); a##s_##3 = GL_A(3, kt_); b##s_##0 = GL_B(0, kt_); b##s_##1 = GL_B(1, kt_); b##s_##2 = GL_B(2, kt_); b##s_##3 = GL_B(3, kt_); }
; #define LDS_STORE(s_, buf_) if (VAR != 2) { LDS_ST1(sA, 0, buf_, a##s_##0) LDS_ST1(sA, 1, buf_, a##s_##1) LDS_ST1(sA, 2, buf_, a##s_##2) LDS_ST1(sA, 3, buf_, a##s_##3) LDS_ST1(sB, 0, buf_, b##s_##0) LDS_ST1(sB, 1, buf_, b##s_##1) LDS_ST1(sB, 2, buf_, b##s_##2) LDS_ST1(sB, 3, buf_, b##s_##3) }
;     ...
;   GL_LOAD(0, 0)
;   GL_LOAD(1, 1)
;   LDS_STORE(0, 0)
;   if (VAR != 4) __syncthreads();
; #pragma unroll
;   for (int kt = 0; kt < nk; kt += 2) {
;     if (kt + 2 < nk) { GL_LOAD(0, kt + 2) }
;     MMA_TILE(0)
;     LDS_STORE(1, 1)
;     if (VAR != 4) __syncthreads();
;     if (kt + 3 < nk) { GL_LOAD(1, kt + 3) }
;     MMA_TILE(1)
;     if (kt + 2 < nk) { LDS_STORE(0, 0) }
;     if (VAR != 4) __syncthreads();
;   }
	v_mfma_f32_16x16x32_f16 v[138:141], v[202:205], v[198:201], v[138:141]
	v_mfma_f32_16x16x32_f16 v[92:95], v[202:205], v[206:209], v[92:95]
	v_mfma_f32_16x16x32_f16 v[142:145], v[210:213], v[198:201], v[142:145]
	v_mfma_f32_16x16x32_f16 v[158:161], v[210:213], v[206:209], v[158:161]
	v_mfma_f32_16x16x32_f16 v[166:169], v[202:205], v[220:223], v[166:169]
	v_mfma_f32_16x16x32_f16 v[68:71], v[202:205], v[228:231], v[68:71]
	ds_read_b128 v[202:205], v136 offset:32768
	v_mfma_f32_16x16x32_f16 v[190:193], v[210:213], v[220:223], v[190:193]
	v_mfma_f32_16x16x32_f16 v[76:79], v[210:213], v[228:231], v[76:79]
	ds_read_b128 v[210:213], v136 offset:34816
	v_mfma_f32_16x16x32_f16 v[154:157], v[224:227], v[198:201], v[154:157]
	v_mfma_f32_16x16x32_f16 v[162:165], v[224:227], v[206:209], v[162:165]
	v_mfma_f32_16x16x32_f16 v[64:67], v[232:235], v[198:201], v[64:67]
	ds_read_b128 v[198:201], v133
	v_mfma_f32_16x16x32_f16 v[72:75], v[232:235], v[206:209], v[72:75]
	ds_read_b128 v[206:209], v133 offset:2048
	v_mfma_f32_16x16x32_f16 v[194:197], v[224:227], v[220:223], v[194:197]
	v_and_b32_e32 v62, 7, v148
	v_bfe_u32 v63, v148, 4, 3
	v_xor_b32_e32 v63, v63, v62
	v_sub_u32_e32 v63, v63, v62
	v_lshlrev_b32_e32 v62, 4, v63
	v_add_u32_e32 v62, 0x380, v62
	v_ashrrev_i32_e32 v63, 31, v62
	v_mfma_f32_16x16x32_f16 v[84:87], v[224:227], v[228:231], v[84:87]
	ds_read_b128 v[224:227], v136 offset:36864
	v_mfma_f32_16x16x32_f16 v[80:83], v[232:235], v[220:223], v[80:83]
	ds_read_b128 v[220:223], v133 offset:4096
	v_mfma_f32_16x16x32_f16 v[88:91], v[232:235], v[228:231], v[88:91]
	ds_read_b128 v[228:231], v133 offset:6144
	s_waitcnt lgkmcnt(4)
	v_mfma_f32_16x16x32_f16 v[138:141], v[202:205], v[198:201], v[138:141]
	ds_read_b128 v[232:235], v136 offset:38912
	s_waitcnt lgkmcnt(4)
	v_mfma_f32_16x16x32_f16 v[92:95], v[202:205], v[206:209], v[92:95]
	v_lshl_add_u64 v[32:33], v[108:109], 0, v[62:63]
	s_mov_b32 m0, s61
	s_nop 0
	global_load_lds_dwordx4 v[32:33], off
	v_mfma_f32_16x16x32_f16 v[142:145], v[210:213], v[198:201], v[142:145]
	v_lshl_add_u64 v[36:37], v[110:111], 0, v[62:63]
	s_mov_b32 m0, s69
	s_nop 0
	global_load_lds_dwordx4 v[36:37], off
	v_mfma_f32_16x16x32_f16 v[158:161], v[210:213], v[206:209], v[158:161]
	v_lshl_add_u64 v[40:41], v[112:113], 0, v[62:63]
	s_mov_b32 m0, s73
	s_nop 0
	global_load_lds_dwordx4 v[40:41], off
	s_waitcnt lgkmcnt(2)
	v_mfma_f32_16x16x32_f16 v[166:169], v[202:205], v[220:223], v[166:169]
	v_lshl_add_u64 v[44:45], v[114:115], 0, v[62:63]
	s_mov_b32 m0, s65
	s_nop 0
	global_load_lds_dwordx4 v[44:45], off
	s_waitcnt lgkmcnt(1)
	v_mfma_f32_16x16x32_f16 v[68:71], v[202:205], v[228:231], v[68:71]
	ds_read_b128 v[202:205], v135 offset:32768
	v_mfma_f32_16x16x32_f16 v[190:193], v[210:213], v[220:223], v[190:193]
	v_lshl_add_u64 v[48:49], v[116:117], 0, v[62:63]
	s_mov_b32 m0, s63
	s_nop 0
	global_load_lds_dwordx4 v[48:49], off
	v_mfma_f32_16x16x32_f16 v[76:79], v[210:213], v[228:231], v[76:79]
	ds_read_b128 v[210:213], v135 offset:34816
	v_mfma_f32_16x16x32_f16 v[154:157], v[224:227], v[198:201], v[154:157]
	v_lshl_add_u64 v[52:53], v[118:119], 0, v[62:63]
	s_mov_b32 m0, s71
	s_nop 0
	global_load_lds_dwordx4 v[52:53], off
	v_mfma_f32_16x16x32_f16 v[162:165], v[224:227], v[206:209], v[162:165]
	v_lshl_add_u64 v[56:57], v[120:121], 0, v[62:63]
	s_mov_b32 m0, s75
	s_nop 0
	global_load_lds_dwordx4 v[56:57], off
	s_waitcnt lgkmcnt(2)
	v_mfma_f32_16x16x32_f16 v[64:67], v[232:235], v[198:201], v[64:67]
	ds_read_b128 v[198:201], v134
	v_mfma_f32_16x16x32_f16 v[72:75], v[232:235], v[206:209], v[72:75]
	ds_read_b128 v[206:209], v134 offset:2048
	v_mfma_f32_16x16x32_f16 v[194:197], v[224:227], v[220:223], v[194:197]
	v_lshl_add_u64 v[60:61], v[122:123], 0, v[62:63]
	s_mov_b32 m0, s67
	s_nop 0
	global_load_lds_dwordx4 v[60:61], off
	v_mfma_f32_16x16x32_f16 v[84:87], v[224:227], v[228:231], v[84:87]
	ds_read_b128 v[224:227], v135 offset:36864
	v_mfma_f32_16x16x32_f16 v[80:83], v[232:235], v[220:223], v[80:83]
	ds_read_b128 v[220:223], v134 offset:4096
	v_mfma_f32_16x16x32_f16 v[88:91], v[232:235], v[228:231], v[88:91]
	ds_read_b128 v[228:231], v134 offset:6144
	ds_read_b128 v[232:235], v135 offset:38912
	s_waitcnt vmcnt(0) lgkmcnt(0)
	s_barrier
	v_mfma_f32_16x16x32_f16 v[138:141], v[202:205], v[198:201], v[138:141]
	v_mfma_f32_16x16x32_f16 v[92:95], v[202:205], v[206:209], v[92:95]
	v_mfma_f32_16x16x32_f16 v[142:145], v[210:213], v[198:201], v[142:145]
	v_mfma_f32_16x16x32_f16 v[158:161], v[210:213], v[206:209], v[158:161]
	v_mfma_f32_16x16x32_f16 v[166:169], v[202:205], v[220:223], v[166:169]
	v_mfma_f32_16x16x32_f16 v[68:71], v[202:205], v[228:231], v[68:71]
	ds_read_b128 v[202:205], v136 offset:49152
	v_mfma_f32_16x16x32_f16 v[190:193], v[210:213], v[220:223], v[190:193]
	v_mfma_f32_16x16x32_f16 v[76:79], v[210:213], v[228:231], v[76:79]
	ds_read_b128 v[210:213], v136 offset:51200
	v_mfma_f32_16x16x32_f16 v[154:157], v[224:227], v[198:201], v[154:157]
	v_mfma_f32_16x16x32_f16 v[162:165], v[224:227], v[206:209], v[162:165]
	v_mfma_f32_16x16x32_f16 v[64:67], v[232:235], v[198:201], v[64:67]
	ds_read_b128 v[198:201], v133 offset:16384
	v_mfma_f32_16x16x32_f16 v[72:75], v[232:235], v[206:209], v[72:75]
	ds_read_b128 v[206:209], v133 offset:18432
	v_mfma_f32_16x16x32_f16 v[194:197], v[224:227], v[220:223], v[194:197]
	v_and_b32_e32 v30, 7, v148
	v_bfe_u32 v31, v148, 4, 3
	v_xor_b32_e32 v31, v31, v30
	v_sub_u32_e32 v31, v31, v30
	v_lshlrev_b32_e32 v30, 4, v31
	v_add_u32_e32 v30, 0x400, v30
	v_ashrrev_i32_e32 v31, 31, v30
	v_mfma_f32_16x16x32_f16 v[84:87], v[224:227], v[228:231], v[84:87]
	ds_read_b128 v[224:227], v136 offset:53248
	v_mfma_f32_16x16x32_f16 v[80:83], v[232:235], v[220:223], v[80:83]
	ds_read_b128 v[220:223], v133 offset:20480
	v_mfma_f32_16x16x32_f16 v[88:91], v[232:235], v[228:231], v[88:91]
	ds_read_b128 v[228:231], v133 offset:22528
	s_waitcnt lgkmcnt(4)
; #define GL_LOAD(s_, kt_) if (VAR != 1) { a##s_##0 = GL_A(0, kt_); a##s_##1 = GL_A(1, kt_); a##s_##2 = GL_A(2, kt_); a##s_##3 = GL_A(3, kt_); b##s_##0 = GL_B(0, kt_); b##s_##1 = GL_B(1, kt_); b##s_##2 = GL_B(2, kt_); b##s_##3 = GL_B(3, kt_); }
; #define LDS_STORE(s_, buf_) if (VAR != 2) { LDS_ST1(sA, 0, buf_, a##s_##0) LDS_ST1(sA, 1, buf_, a##s_##1) LDS_ST1(sA, 2, buf_, a##s_##2) LDS_ST1(sA, 3, buf_, a##s_##3) LDS_ST1(sB, 0, buf_, b##s_##0) LDS_ST1(sB, 1, buf_, b##s_##1) LDS_ST1(sB, 2, buf_, b##s_##2) LDS_ST1(sB, 3, buf_, b##s_##3) }
;     ...
;   GL_LOAD(0, 0)
;   GL_LOAD(1, 1)
;   LDS_STORE(0, 0)
;   if (VAR != 4) __syncthreads();
; #pragma unroll
;   for (int kt = 0; kt < nk; kt += 2) {
;     if (kt + 2 < nk) { GL_LOAD(0, kt + 2) }
;     MMA_TILE(0)
;     LDS_STORE(1, 1)
;     if (VAR != 4) __syncthreads();
;     if (kt + 3 < nk) { GL_LOAD(1, kt + 3) }
;     MMA_TILE(1)
;     if (kt + 2 < nk) { LDS_STORE(0, 0) }
;     if (VAR != 4) __syncthreads();
;   }
	v_mfma_f32_16x16x32_f16 v[138:141], v[202:205], v[198:201], v[138:141]
	ds_read_b128 v[232:235], v136 offset:55296
	s_waitcnt lgkmcnt(4)
	v_mfma_f32_16x16x32_f16 v[92:95], v[202:205], v[206:209], v[92:95]
	v_lshl_add_u64 v[0:1], v[108:109], 0, v[30:31]
	s_mov_b32 m0, s60
	s_nop 0
	global_load_lds_dwordx4 v[0:1], off
	v_mfma_f32_16x16x32_f16 v[142:145], v[210:213], v[198:201], v[142:145]
	v_lshl_add_u64 v[4:5], v[110:111], 0, v[30:31]
	s_mov_b32 m0, s68
	s_nop 0
	global_load_lds_dwordx4 v[4:5], off
	v_mfma_f32_16x16x32_f16 v[158:161], v[210:213], v[206:209], v[158:161]
	v_lshl_add_u64 v[8:9], v[112:113], 0, v[30:31]
	s_mov_b32 m0, s72
	s_nop 0
	global_load_lds_dwordx4 v[8:9], off
	s_waitcnt lgkmcnt(2)
	v_mfma_f32_16x16x32_f16 v[166:169], v[202:205], v[220:223], v[166:169]
	v_lshl_add_u64 v[12:13], v[114:115], 0, v[30:31]
	s_mov_b32 m0, s64
	s_nop 0
	global_load_lds_dwordx4 v[12:13], off
	s_waitcnt lgkmcnt(1)
	v_mfma_f32_16x16x32_f16 v[68:71], v[202:205], v[228:231], v[68:71]
	ds_read_b128 v[202:205], v135 offset:49152
	v_mfma_f32_16x16x32_f16 v[190:193], v[210:213], v[220:223], v[190:193]
	v_lshl_add_u64 v[16:17], v[116:117], 0, v[30:31]
	s_mov_b32 m0, s62
	s_nop 0
	global_load_lds_dwordx4 v[16:17], off
	v_mfma_f32_16x16x32_f16 v[76:79], v[210:213], v[228:231], v[76:79]
	ds_read_b128 v[210:213], v135 offset:51200
	v_mfma_f32_16x16x32_f16 v[154:157], v[224:227], v[198:201], v[154:157]
	v_lshl_add_u64 v[20:21], v[118:119], 0, v[30:31]
	s_mov_b32 m0, s70
	s_nop 0
	global_load_lds_dwordx4 v[20:21], off
	v_mfma_f32_16x16x32_f16 v[162:165], v[224:227], v[206:209], v[162:165]
	v_lshl_add_u64 v[24:25], v[120:121], 0, v[30:31]
	s_mov_b32 m0, s74
	s_nop 0
	global_load_lds_dwordx4 v[24:25], off
	s_waitcnt lgkmcnt(2)
	v_mfma_f32_16x16x32_f16 v[64:67], v[232:235], v[198:201], v[64:67]
	ds_read_b128 v[198:201], v134 offset:16384
	v_mfma_f32_16x16x32_f16 v[72:75], v[232:235], v[206:209], v[72:75]
	ds_read_b128 v[206:209], v134 offset:18432
	v_mfma_f32_16x16x32_f16 v[194:197], v[224:227], v[220:223], v[194:197]
	v_lshl_add_u64 v[28:29], v[122:123], 0, v[30:31]
	s_mov_b32 m0, s66
	s_nop 0
	global_load_lds_dwordx4 v[28:29], off
	v_mfma_f32_16x16x32_f16 v[84:87], v[224:227], v[228:231], v[84:87]
	ds_read_b128 v[224:227], v135 offset:53248
	v_mfma_f32_16x16x32_f16 v[80:83], v[232:235], v[220:223], v[80:83]
	ds_read_b128 v[220:223], v134 offset:20480
	v_mfma_f32_16x16x32_f16 v[88:91], v[232:235], v[228:231], v[88:91]
	ds_read_b128 v[228:231], v134 offset:22528
	s_waitcnt lgkmcnt(4)
	v_mfma_f32_16x16x32_f16 v[138:141], v[202:205], v[198:201], v[138:141]
	ds_read_b128 v[232:235], v135 offset:55296
	s_waitcnt vmcnt(0) lgkmcnt(0)
	s_barrier
	v_mfma_f32_16x16x32_f16 v[142:145], v[210:213], v[198:201], v[142:145]
	ds_read_b128 v[0:3], v133
	v_mfma_f32_16x16x32_f16 v[158:161], v[210:213], v[206:209], v[158:161]
	ds_read_b128 v[4:7], v136 offset:32768
	v_mfma_f32_16x16x32_f16 v[154:157], v[224:227], v[198:201], v[154:157]
	ds_read_b128 v[8:11], v133 offset:2048
	v_mfma_f32_16x16x32_f16 v[162:165], v[224:227], v[206:209], v[162:165]
	ds_read_b128 v[12:15], v136 offset:34816
	v_mfma_f32_16x16x32_f16 v[190:193], v[210:213], v[220:223], v[190:193]
	ds_read_b128 v[16:19], v133 offset:4096
	v_mfma_f32_16x16x32_f16 v[210:213], v[210:213], v[228:231], v[76:79]
	ds_read_b128 v[20:23], v136 offset:36864
	v_mfma_f32_16x16x32_f16 v[194:197], v[224:227], v[220:223], v[194:197]
	ds_read_b128 v[24:27], v133 offset:6144
	v_mfma_f32_16x16x32_f16 v[224:227], v[224:227], v[228:231], v[84:87]
	ds_read_b128 v[28:31], v136 offset:38912
	v_mfma_f32_16x16x32_f16 v[198:201], v[232:235], v[198:201], v[64:67]
	s_nop 2
	v_mfma_f32_16x16x32_f16 v[236:239], v[202:205], v[206:209], v[92:95]
	v_mfma_f32_16x16x32_f16 v[206:209], v[232:235], v[206:209], v[72:75]
	v_mfma_f32_16x16x32_f16 v[166:169], v[202:205], v[220:223], v[166:169]
	v_mfma_f32_16x16x32_f16 v[220:223], v[232:235], v[220:223], v[80:83]
	v_mfma_f32_16x16x32_f16 v[202:205], v[202:205], v[228:231], v[68:71]
	v_mfma_f32_16x16x32_f16 v[228:231], v[232:235], v[228:231], v[88:91]
	ds_read_b128 v[232:235], v135 offset:38912
	s_nop 0
	s_waitcnt lgkmcnt(7)
	v_mfma_f32_16x16x32_f16 v[138:141], v[4:7], v[0:3], v[138:141]
	s_waitcnt lgkmcnt(5)
	v_mfma_f32_16x16x32_f16 v[142:145], v[12:15], v[0:3], v[142:145]
	s_waitcnt lgkmcnt(3)
	v_mfma_f32_16x16x32_f16 v[154:157], v[20:23], v[0:3], v[154:157]
	s_waitcnt lgkmcnt(1)
	v_mfma_f32_16x16x32_f16 v[0:3], v[28:31], v[0:3], v[198:201]
	v_mfma_f32_16x16x32_f16 v[198:201], v[4:7], v[8:11], v[236:239]
	v_mfma_f32_16x16x32_f16 v[158:161], v[12:15], v[8:11], v[158:161]
	v_and_b32_e32 v62, 7, v148
	v_bfe_u32 v63, v148, 4, 3
	v_xor_b32_e32 v63, v63, v62
	v_sub_u32_e32 v63, v63, v62
	v_lshlrev_b32_e32 v62, 4, v63
	v_add_u32_e32 v62, 0x480, v62
	v_ashrrev_i32_e32 v63, 31, v62
	v_lshl_add_u64 v[32:33], v[108:109], 0, v[62:63]
	s_mov_b32 m0, s61
	s_nop 0
	global_load_lds_dwordx4 v[32:33], off
	v_mfma_f32_16x16x32_f16 v[166:169], v[4:7], v[16:19], v[166:169]
	v_lshl_add_u64 v[36:37], v[110:111], 0, v[62:63]
	s_mov_b32 m0, s69
	s_nop 0
	global_load_lds_dwordx4 v[36:37], off
	v_lshl_add_u64 v[40:41], v[112:113], 0, v[62:63]
	s_mov_b32 m0, s73
	s_nop 0
	global_load_lds_dwordx4 v[40:41], off
	v_mfma_f32_16x16x32_f16 v[4:7], v[4:7], v[24:27], v[202:205]
	s_nop 2
	ds_read_b128 v[202:205], v135 offset:32768
	v_lshl_add_u64 v[44:45], v[114:115], 0, v[62:63]
	s_mov_b32 m0, s65
	s_nop 0
	global_load_lds_dwordx4 v[44:45], off
	v_mfma_f32_16x16x32_f16 v[190:193], v[12:15], v[16:19], v[190:193]
	v_lshl_add_u64 v[48:49], v[116:117], 0, v[62:63]
	s_mov_b32 m0, s63
	s_nop 0
	global_load_lds_dwordx4 v[48:49], off
	v_mfma_f32_16x16x32_f16 v[12:15], v[12:15], v[24:27], v[210:213]
	s_nop 2
	ds_read_b128 v[210:213], v135 offset:34816
	v_lshl_add_u64 v[52:53], v[118:119], 0, v[62:63]
	s_mov_b32 m0, s71
	s_nop 0
	global_load_lds_dwordx4 v[52:53], off
	v_mfma_f32_16x16x32_f16 v[162:165], v[20:23], v[8:11], v[162:165]
	v_lshl_add_u64 v[56:57], v[120:121], 0, v[62:63]
	s_mov_b32 m0, s75
	s_nop 0
	global_load_lds_dwordx4 v[56:57], off
	v_lshl_add_u64 v[60:61], v[122:123], 0, v[62:63]
	s_mov_b32 m0, s67
	s_nop 0
	global_load_lds_dwordx4 v[60:61], off
	v_mfma_f32_16x16x32_f16 v[8:11], v[28:31], v[8:11], v[206:209]
	s_nop 2
	ds_read_b128 v[206:209], v134 offset:2048
	v_mfma_f32_16x16x32_f16 v[194:197], v[20:23], v[16:19], v[194:197]
	v_mfma_f32_16x16x32_f16 v[20:23], v[20:23], v[24:27], v[224:227]
	s_nop 2
	ds_read_b128 v[224:227], v135 offset:36864
	v_mfma_f32_16x16x32_f16 v[16:19], v[28:31], v[16:19], v[220:223]
	s_nop 2
	ds_read_b128 v[220:223], v134 offset:4096
	v_mfma_f32_16x16x32_f16 v[24:27], v[28:31], v[24:27], v[228:231]
	ds_read_b128 v[28:31], v134
	s_waitcnt lgkmcnt(0)
	v_mfma_f32_16x16x32_f16 v[138:141], v[202:205], v[28:31], v[138:141]
	ds_read_b128 v[228:231], v134 offset:6144
	s_waitcnt vmcnt(0) lgkmcnt(0)
	s_barrier
; #define GL_LOAD(s_, kt_) if (VAR != 1) { a##s_##0 = GL_A(0, kt_); a##s_##1 = GL_A(1, kt_); a##s_##2 = GL_A(2, kt_); a##s_##3 = GL_A(3, kt_); b##s_##0 = GL_B(0, kt_); b##s_##1 = GL_B(1, kt_); b##s_##2 = GL_B(2, kt_); b##s_##3 = GL_B(3, kt_); }
; #define LDS_STORE(s_, buf_) if (VAR != 2) { LDS_ST1(sA, 0, buf_, a##s_##0) LDS_ST1(sA, 1, buf_, a##s_##1) LDS_ST1(sA, 2, buf_, a##s_##2) LDS_ST1(sA, 3, buf_, a##s_##3) LDS_ST1(sB, 0, buf_, b##s_##0) LDS_ST1(sB, 1, buf_, b##s_##1) LDS_ST1(sB, 2, buf_, b##s_##2) LDS_ST1(sB, 3, buf_, b##s_##3) }
;     ...
;   GL_LOAD(0, 0)
;   GL_LOAD(1, 1)
;   LDS_STORE(0, 0)
;   if (VAR != 4) __syncthreads();
; #pragma unroll
;   for (int kt = 0; kt < nk; kt += 2) {
;     if (kt + 2 < nk) { GL_LOAD(0, kt + 2) }
;     MMA_TILE(0)
;     LDS_STORE(1, 1)
;     if (VAR != 4) __syncthreads();
;     if (kt + 3 < nk) { GL_LOAD(1, kt + 3) }
;     MMA_TILE(1)
;     if (kt + 2 < nk) { LDS_STORE(0, 0) }
;     if (VAR != 4) __syncthreads();
;   }
	v_mfma_f32_16x16x32_f16 v[142:145], v[210:213], v[28:31], v[142:145]
	ds_read_b128 v[32:35], v133 offset:16384
	v_mfma_f32_16x16x32_f16 v[158:161], v[210:213], v[206:209], v[158:161]
	ds_read_b128 v[36:39], v136 offset:49152
	v_mfma_f32_16x16x32_f16 v[154:157], v[224:227], v[28:31], v[154:157]
	ds_read_b128 v[40:43], v133 offset:18432
	v_mfma_f32_16x16x32_f16 v[162:165], v[224:227], v[206:209], v[162:165]
	ds_read_b128 v[44:47], v136 offset:51200
	v_mfma_f32_16x16x32_f16 v[190:193], v[210:213], v[220:223], v[190:193]
	ds_read_b128 v[48:51], v133 offset:20480
	v_mfma_f32_16x16x32_f16 v[210:213], v[210:213], v[228:231], v[12:15]
	ds_read_b128 v[52:55], v136 offset:53248
	v_mfma_f32_16x16x32_f16 v[194:197], v[224:227], v[220:223], v[194:197]
	ds_read_b128 v[56:59], v133 offset:22528
	v_mfma_f32_16x16x32_f16 v[224:227], v[224:227], v[228:231], v[20:23]
	ds_read_b128 v[60:63], v136 offset:55296
	v_mfma_f32_16x16x32_f16 v[236:239], v[232:235], v[28:31], v[0:3]
	v_mfma_f32_16x16x32_f16 v[198:201], v[202:205], v[206:209], v[198:201]
	v_mfma_f32_16x16x32_f16 v[206:209], v[232:235], v[206:209], v[8:11]
	v_mfma_f32_16x16x32_f16 v[166:169], v[202:205], v[220:223], v[166:169]
	v_mfma_f32_16x16x32_f16 v[220:223], v[232:235], v[220:223], v[16:19]
	v_mfma_f32_16x16x32_f16 v[202:205], v[202:205], v[228:231], v[4:7]
	v_mfma_f32_16x16x32_f16 v[228:231], v[232:235], v[228:231], v[24:27]
	ds_read_b128 v[232:235], v135 offset:55296
	s_nop 1
	s_waitcnt lgkmcnt(7)
	v_mfma_f32_16x16x32_f16 v[138:141], v[36:39], v[32:35], v[138:141]
	s_waitcnt lgkmcnt(6)
	v_mfma_f32_16x16x32_f16 v[198:201], v[36:39], v[40:43], v[198:201]
	s_waitcnt lgkmcnt(5)
	v_mfma_f32_16x16x32_f16 v[142:145], v[44:47], v[32:35], v[142:145]
	v_mfma_f32_16x16x32_f16 v[158:161], v[44:47], v[40:43], v[158:161]
	s_waitcnt lgkmcnt(4)
	v_mfma_f32_16x16x32_f16 v[166:169], v[36:39], v[48:51], v[166:169]
	v_and_b32_e32 v94, 7, v148
	v_bfe_u32 v95, v148, 4, 3
	v_xor_b32_e32 v95, v95, v94
	v_sub_u32_e32 v95, v95, v94
	v_lshlrev_b32_e32 v94, 4, v95
	v_add_u32_e32 v94, 0x500, v94
	v_ashrrev_i32_e32 v95, 31, v94
	s_waitcnt lgkmcnt(2)
	v_mfma_f32_16x16x32_f16 v[36:39], v[36:39], v[56:59], v[202:205]
	s_nop 2
	ds_read_b128 v[202:205], v135 offset:49152
	v_lshl_add_u64 v[64:65], v[108:109], 0, v[94:95]
	s_mov_b32 m0, s60
	s_nop 0
	global_load_lds_dwordx4 v[64:65], off
	v_mfma_f32_16x16x32_f16 v[190:193], v[44:47], v[48:51], v[190:193]
	v_lshl_add_u64 v[68:69], v[110:111], 0, v[94:95]
	s_mov_b32 m0, s68
	s_nop 0
	global_load_lds_dwordx4 v[68:69], off
	v_lshl_add_u64 v[72:73], v[112:113], 0, v[94:95]
	s_mov_b32 m0, s72
	s_nop 0
	global_load_lds_dwordx4 v[72:73], off
	v_mfma_f32_16x16x32_f16 v[44:47], v[44:47], v[56:59], v[210:213]
	s_nop 2
	ds_read_b128 v[210:213], v135 offset:51200
	v_mfma_f32_16x16x32_f16 v[154:157], v[52:55], v[32:35], v[154:157]
	v_lshl_add_u64 v[76:77], v[114:115], 0, v[94:95]
	s_mov_b32 m0, s64
	s_nop 0
	global_load_lds_dwordx4 v[76:77], off
	v_mfma_f32_16x16x32_f16 v[162:165], v[52:55], v[40:43], v[162:165]
	v_lshl_add_u64 v[80:81], v[116:117], 0, v[94:95]
	s_mov_b32 m0, s62
	s_nop 0
	global_load_lds_dwordx4 v[80:81], off
	s_waitcnt lgkmcnt(3)
	v_mfma_f32_16x16x32_f16 v[32:35], v[60:63], v[32:35], v[236:239]
	v_lshl_add_u64 v[84:85], v[118:119], 0, v[94:95]
	s_mov_b32 m0, s70
	s_nop 0
	global_load_lds_dwordx4 v[84:85], off
	v_mfma_f32_16x16x32_f16 v[40:43], v[60:63], v[40:43], v[206:209]
	s_nop 2
	ds_read_b128 v[206:209], v134 offset:18432
	v_mfma_f32_16x16x32_f16 v[194:197], v[52:55], v[48:51], v[194:197]
	v_lshl_add_u64 v[88:89], v[120:121], 0, v[94:95]
	s_mov_b32 m0, s74
	s_nop 0
	global_load_lds_dwordx4 v[88:89], off
	v_mfma_f32_16x16x32_f16 v[52:55], v[52:55], v[56:59], v[224:227]
	s_nop 2
	ds_read_b128 v[224:227], v135 offset:53248
	v_mfma_f32_16x16x32_f16 v[48:51], v[60:63], v[48:51], v[220:223]
	s_nop 2
	ds_read_b128 v[220:223], v134 offset:20480
	v_mfma_f32_16x16x32_f16 v[56:59], v[60:63], v[56:59], v[228:231]
	ds_read_b128 v[60:63], v134 offset:16384
	s_waitcnt lgkmcnt(0)
	v_mfma_f32_16x16x32_f16 v[138:141], v[202:205], v[60:63], v[138:141]
	ds_read_b128 v[228:231], v134 offset:22528
	v_lshl_add_u64 v[92:93], v[122:123], 0, v[94:95]
	s_mov_b32 m0, s66
	s_nop 0
	global_load_lds_dwordx4 v[92:93], off
	s_waitcnt vmcnt(0) lgkmcnt(0)
	s_barrier
; #define GL_LOAD(s_, kt_) if (VAR != 1) { a##s_##0 = GL_A(0, kt_); a##s_##1 = GL_A(1, kt_); a##s_##2 = GL_A(2, kt_); a##s_##3 = GL_A(3, kt_); b##s_##0 = GL_B(0, kt_); b##s_##1 = GL_B(1, kt_); b##s_##2 = GL_B(2, kt_); b##s_##3 = GL_B(3, kt_); }
; #define LDS_STORE(s_, buf_) if (VAR != 2) { LDS_ST1(sA, 0, buf_, a##s_##0) LDS_ST1(sA, 1, buf_, a##s_##1) LDS_ST1(sA, 2, buf_, a##s_##2) LDS_ST1(sA, 3, buf_, a##s_##3) LDS_ST1(sB, 0, buf_, b##s_##0) LDS_ST1(sB, 1, buf_, b##s_##1) LDS_ST1(sB, 2, buf_, b##s_##2) LDS_ST1(sB, 3, buf_, b##s_##3) }
;     ...
;   GL_LOAD(0, 0)
;   GL_LOAD(1, 1)
;   LDS_STORE(0, 0)
;   if (VAR != 4) __syncthreads();
; #pragma unroll
;   for (int kt = 0; kt < nk; kt += 2) {
;     if (kt + 2 < nk) { GL_LOAD(0, kt + 2) }
;     MMA_TILE(0)
;     LDS_STORE(1, 1)
;     if (VAR != 4) __syncthreads();
;     if (kt + 3 < nk) { GL_LOAD(1, kt + 3) }
;     MMA_TILE(1)
;     if (kt + 2 < nk) { LDS_STORE(0, 0) }
;     if (VAR != 4) __syncthreads();
;   }
	v_mfma_f32_16x16x32_f16 v[142:145], v[210:213], v[60:63], v[142:145]
	ds_read_b128 v[64:67], v133
	v_mfma_f32_16x16x32_f16 v[158:161], v[210:213], v[206:209], v[158:161]
	ds_read_b128 v[68:71], v136 offset:32768
	v_mfma_f32_16x16x32_f16 v[154:157], v[224:227], v[60:63], v[154:157]
	ds_read_b128 v[72:75], v133 offset:2048
	v_mfma_f32_16x16x32_f16 v[162:165], v[224:227], v[206:209], v[162:165]
	ds_read_b128 v[76:79], v136 offset:34816
	v_mfma_f32_16x16x32_f16 v[190:193], v[210:213], v[220:223], v[190:193]
	ds_read_b128 v[80:83], v133 offset:4096
	v_mfma_f32_16x16x32_f16 v[210:213], v[210:213], v[228:231], v[44:47]
	ds_read_b128 v[84:87], v136 offset:36864
	v_mfma_f32_16x16x32_f16 v[194:197], v[224:227], v[220:223], v[194:197]
	ds_read_b128 v[88:91], v133 offset:6144
	v_mfma_f32_16x16x32_f16 v[224:227], v[224:227], v[228:231], v[52:55]
	ds_read_b128 v[92:95], v136 offset:38912
	v_mfma_f32_16x16x32_f16 v[236:239], v[232:235], v[60:63], v[32:35]
	s_nop 0
	v_mfma_f32_16x16x32_f16 v[198:201], v[202:205], v[206:209], v[198:201]
	v_mfma_f32_16x16x32_f16 v[206:209], v[232:235], v[206:209], v[40:43]
	v_mfma_f32_16x16x32_f16 v[166:169], v[202:205], v[220:223], v[166:169]
	v_mfma_f32_16x16x32_f16 v[220:223], v[232:235], v[220:223], v[48:51]
	v_mfma_f32_16x16x32_f16 v[202:205], v[202:205], v[228:231], v[36:39]
	v_mfma_f32_16x16x32_f16 v[228:231], v[232:235], v[228:231], v[56:59]
	ds_read_b128 v[232:235], v135 offset:38912
	s_nop 1
	s_waitcnt lgkmcnt(7)
	v_mfma_f32_16x16x32_f16 v[138:141], v[68:71], v[64:67], v[138:141]
	s_waitcnt lgkmcnt(6)
	v_mfma_f32_16x16x32_f16 v[198:201], v[68:71], v[72:75], v[198:201]
	s_waitcnt lgkmcnt(5)
	v_mfma_f32_16x16x32_f16 v[142:145], v[76:79], v[64:67], v[142:145]
	v_mfma_f32_16x16x32_f16 v[158:161], v[76:79], v[72:75], v[158:161]
	s_waitcnt lgkmcnt(4)
	v_mfma_f32_16x16x32_f16 v[166:169], v[68:71], v[80:83], v[166:169]
	v_and_b32_e32 v10, 7, v148
	v_bfe_u32 v11, v148, 4, 3
	v_xor_b32_e32 v11, v11, v10
	v_sub_u32_e32 v11, v11, v10
	v_lshlrev_b32_e32 v10, 4, v11
	v_add_u32_e32 v10, 0x580, v10
	v_ashrrev_i32_e32 v11, 31, v10
	v_lshl_add_u64 v[28:29], v[108:109], 0, v[10:11]
	s_mov_b32 m0, s61
	s_nop 0
	global_load_lds_dwordx4 v[28:29], off
	s_waitcnt lgkmcnt(2)
	v_mfma_f32_16x16x32_f16 v[68:71], v[68:71], v[88:91], v[202:205]
	s_nop 2
	ds_read_b128 v[202:205], v135 offset:32768
	v_lshl_add_u64 v[24:25], v[110:111], 0, v[10:11]
	s_mov_b32 m0, s69
	s_nop 0
	global_load_lds_dwordx4 v[24:25], off
	v_mfma_f32_16x16x32_f16 v[190:193], v[76:79], v[80:83], v[190:193]
	v_lshl_add_u64 v[12:13], v[112:113], 0, v[10:11]
	s_mov_b32 m0, s73
	s_nop 0
	global_load_lds_dwordx4 v[12:13], off
	v_lshl_add_u64 v[16:17], v[114:115], 0, v[10:11]
	s_mov_b32 m0, s65
	s_nop 0
	global_load_lds_dwordx4 v[16:17], off
	v_mfma_f32_16x16x32_f16 v[76:79], v[76:79], v[88:91], v[210:213]
	s_nop 2
	ds_read_b128 v[210:213], v135 offset:34816
	v_mfma_f32_16x16x32_f16 v[154:157], v[84:87], v[64:67], v[154:157]
	v_lshl_add_u64 v[20:21], v[116:117], 0, v[10:11]
	s_mov_b32 m0, s63
	s_nop 0
	global_load_lds_dwordx4 v[20:21], off
	v_mfma_f32_16x16x32_f16 v[162:165], v[84:87], v[72:75], v[162:165]
	v_lshl_add_u64 v[0:1], v[118:119], 0, v[10:11]
	s_mov_b32 m0, s71
	s_nop 0
	global_load_lds_dwordx4 v[0:1], off
	s_waitcnt lgkmcnt(3)
	v_mfma_f32_16x16x32_f16 v[64:67], v[92:95], v[64:67], v[236:239]
	v_lshl_add_u64 v[4:5], v[120:121], 0, v[10:11]
	s_mov_b32 m0, s75
	s_nop 0
	global_load_lds_dwordx4 v[4:5], off
	v_mfma_f32_16x16x32_f16 v[72:75], v[92:95], v[72:75], v[206:209]
	s_nop 2
	ds_read_b128 v[206:209], v134 offset:2048
	v_mfma_f32_16x16x32_f16 v[194:197], v[84:87], v[80:83], v[194:197]
	v_lshl_add_u64 v[8:9], v[122:123], 0, v[10:11]
	s_mov_b32 m0, s67
	s_nop 0
	global_load_lds_dwordx4 v[8:9], off
	v_mfma_f32_16x16x32_f16 v[84:87], v[84:87], v[88:91], v[224:227]
	s_nop 2
	ds_read_b128 v[224:227], v135 offset:36864
	v_mfma_f32_16x16x32_f16 v[80:83], v[92:95], v[80:83], v[220:223]
	s_nop 2
	ds_read_b128 v[220:223], v134 offset:4096
	v_mfma_f32_16x16x32_f16 v[88:91], v[92:95], v[88:91], v[228:231]
	ds_read_b128 v[92:95], v134
	s_nop 1
	ds_read_b128 v[228:231], v134 offset:6144
	s_waitcnt vmcnt(0) lgkmcnt(0)
	s_barrier
	v_mfma_f32_16x16x32_f16 v[138:141], v[202:205], v[92:95], v[138:141]
	v_mfma_f32_16x16x32_f16 v[142:145], v[210:213], v[92:95], v[142:145]
	v_mfma_f32_16x16x32_f16 v[154:157], v[224:227], v[92:95], v[154:157]
	v_mfma_f32_16x16x32_f16 v[64:67], v[232:235], v[92:95], v[64:67]
	v_mfma_f32_16x16x32_f16 v[92:95], v[202:205], v[206:209], v[198:201]
	s_nop 2
	ds_read_b128 v[198:201], v133 offset:16384
	v_mfma_f32_16x16x32_f16 v[158:161], v[210:213], v[206:209], v[158:161]
	v_mfma_f32_16x16x32_f16 v[166:169], v[202:205], v[220:223], v[166:169]
	v_mfma_f32_16x16x32_f16 v[68:71], v[202:205], v[228:231], v[68:71]
	ds_read_b128 v[202:205], v136 offset:49152
	v_mfma_f32_16x16x32_f16 v[190:193], v[210:213], v[220:223], v[190:193]
	v_mfma_f32_16x16x32_f16 v[76:79], v[210:213], v[228:231], v[76:79]
	ds_read_b128 v[210:213], v136 offset:51200
	v_mfma_f32_16x16x32_f16 v[162:165], v[224:227], v[206:209], v[162:165]
	v_mfma_f32_16x16x32_f16 v[72:75], v[232:235], v[206:209], v[72:75]
	ds_read_b128 v[206:209], v133 offset:18432
	v_mfma_f32_16x16x32_f16 v[194:197], v[224:227], v[220:223], v[194:197]
	v_and_b32_e32 v38, 7, v148
	v_bfe_u32 v39, v148, 4, 3
	v_xor_b32_e32 v39, v39, v38
	v_sub_u32_e32 v39, v39, v38
	v_lshlrev_b32_e32 v38, 4, v39
	v_add_u32_e32 v38, 0x600, v38
	v_ashrrev_i32_e32 v39, 31, v38
	v_mfma_f32_16x16x32_f16 v[84:87], v[224:227], v[228:231], v[84:87]
	ds_read_b128 v[224:227], v136 offset:53248
	v_mfma_f32_16x16x32_f16 v[80:83], v[232:235], v[220:223], v[80:83]
	ds_read_b128 v[220:223], v133 offset:20480
	v_mfma_f32_16x16x32_f16 v[88:91], v[232:235], v[228:231], v[88:91]
	ds_read_b128 v[228:231], v133 offset:22528
	s_waitcnt lgkmcnt(5)
; #define GL_LOAD(s_, kt_) if (VAR != 1) { a##s_##0 = GL_A(0, kt_); a##s_##1 = GL_A(1, kt_); a##s_##2 = GL_A(2, kt_); a##s_##3 = GL_A(3, kt_); b##s_##0 = GL_B(0, kt_); b##s_##1 = GL_B(1, kt_); b##s_##2 = GL_B(2, kt_); b##s_##3 = GL_B(3, kt_); }
; #define LDS_STORE(s_, buf_) if (VAR != 2) { LDS_ST1(sA, 0, buf_, a##s_##0) LDS_ST1(sA, 1, buf_, a##s_##1) LDS_ST1(sA, 2, buf_, a##s_##2) LDS_ST1(sA, 3, buf_, a##s_##3) LDS_ST1(sB, 0, buf_, b##s_##0) LDS_ST1(sB, 1, buf_, b##s_##1) LDS_ST1(sB, 2, buf_, b##s_##2) LDS_ST1(sB, 3, buf_, b##s_##3) }
;     ...
;   GL_LOAD(0, 0)
;   GL_LOAD(1, 1)
;   LDS_STORE(0, 0)
;   if (VAR != 4) __syncthreads();
; #pragma unroll
;   for (int kt = 0; kt < nk; kt += 2) {
;     if (kt + 2 < nk) { GL_LOAD(0, kt + 2) }
;     MMA_TILE(0)
;     LDS_STORE(1, 1)
;     if (VAR != 4) __syncthreads();
;     if (kt + 3 < nk) { GL_LOAD(1, kt + 3) }
;     MMA_TILE(1)
;     if (kt + 2 < nk) { LDS_STORE(0, 0) }
;     if (VAR != 4) __syncthreads();
;   }
	v_mfma_f32_16x16x32_f16 v[138:141], v[202:205], v[198:201], v[138:141]
	ds_read_b128 v[232:235], v136 offset:55296
	s_waitcnt lgkmcnt(4)
	v_mfma_f32_16x16x32_f16 v[92:95], v[202:205], v[206:209], v[92:95]
	v_lshl_add_u64 v[52:53], v[108:109], 0, v[38:39]
	s_mov_b32 m0, s60
	s_nop 0
	global_load_lds_dwordx4 v[52:53], off
	v_mfma_f32_16x16x32_f16 v[142:145], v[210:213], v[198:201], v[142:145]
	v_lshl_add_u64 v[56:57], v[110:111], 0, v[38:39]
	s_mov_b32 m0, s68
	s_nop 0
	global_load_lds_dwordx4 v[56:57], off
	v_mfma_f32_16x16x32_f16 v[158:161], v[210:213], v[206:209], v[158:161]
	v_lshl_add_u64 v[60:61], v[112:113], 0, v[38:39]
	s_mov_b32 m0, s72
	s_nop 0
	global_load_lds_dwordx4 v[60:61], off
	s_waitcnt lgkmcnt(2)
	v_mfma_f32_16x16x32_f16 v[166:169], v[202:205], v[220:223], v[166:169]
	v_lshl_add_u64 v[40:41], v[114:115], 0, v[38:39]
	s_mov_b32 m0, s64
	s_nop 0
	global_load_lds_dwordx4 v[40:41], off
	s_waitcnt lgkmcnt(1)
	v_mfma_f32_16x16x32_f16 v[68:71], v[202:205], v[228:231], v[68:71]
	ds_read_b128 v[202:205], v135 offset:49152
	v_mfma_f32_16x16x32_f16 v[190:193], v[210:213], v[220:223], v[190:193]
	v_lshl_add_u64 v[44:45], v[116:117], 0, v[38:39]
	s_mov_b32 m0, s62
	s_nop 0
	global_load_lds_dwordx4 v[44:45], off
	v_mfma_f32_16x16x32_f16 v[76:79], v[210:213], v[228:231], v[76:79]
	ds_read_b128 v[210:213], v135 offset:51200
	v_mfma_f32_16x16x32_f16 v[154:157], v[224:227], v[198:201], v[154:157]
	v_lshl_add_u64 v[48:49], v[118:119], 0, v[38:39]
	s_mov_b32 m0, s70
	s_nop 0
	global_load_lds_dwordx4 v[48:49], off
	v_mfma_f32_16x16x32_f16 v[162:165], v[224:227], v[206:209], v[162:165]
	v_lshl_add_u64 v[32:33], v[120:121], 0, v[38:39]
	s_mov_b32 m0, s74
	s_nop 0
	global_load_lds_dwordx4 v[32:33], off
	s_waitcnt lgkmcnt(2)
	v_mfma_f32_16x16x32_f16 v[64:67], v[232:235], v[198:201], v[64:67]
	ds_read_b128 v[198:201], v134 offset:16384
	v_mfma_f32_16x16x32_f16 v[72:75], v[232:235], v[206:209], v[72:75]
	ds_read_b128 v[206:209], v134 offset:18432
	v_mfma_f32_16x16x32_f16 v[194:197], v[224:227], v[220:223], v[194:197]
	v_lshl_add_u64 v[36:37], v[122:123], 0, v[38:39]
	s_mov_b32 m0, s66
	s_nop 0
	global_load_lds_dwordx4 v[36:37], off
	v_mfma_f32_16x16x32_f16 v[84:87], v[224:227], v[228:231], v[84:87]
	ds_read_b128 v[224:227], v135 offset:53248
	v_mfma_f32_16x16x32_f16 v[80:83], v[232:235], v[220:223], v[80:83]
	ds_read_b128 v[220:223], v134 offset:20480
	v_mfma_f32_16x16x32_f16 v[88:91], v[232:235], v[228:231], v[88:91]
	ds_read_b128 v[228:231], v134 offset:22528
	ds_read_b128 v[232:235], v135 offset:55296
	s_waitcnt vmcnt(0) lgkmcnt(0)
	s_barrier
	v_mfma_f32_16x16x32_f16 v[138:141], v[202:205], v[198:201], v[138:141]
	v_and_b32_e32 v6, 7, v148
	v_bfe_u32 v7, v148, 4, 3
	v_xor_b32_e32 v7, v7, v6
	v_sub_u32_e32 v7, v7, v6
	v_lshlrev_b32_e32 v6, 4, v7
	v_add_u32_e32 v6, 0x680, v6
	v_ashrrev_i32_e32 v7, 31, v6
	v_mfma_f32_16x16x32_f16 v[92:95], v[202:205], v[206:209], v[92:95]
	global_load_dwordx4 v[60:63], v[108:109], off offset:1792
	v_mfma_f32_16x16x32_f16 v[142:145], v[210:213], v[198:201], v[142:145]
	global_load_dwordx4 v[48:51], v[110:111], off offset:1792
	v_mfma_f32_16x16x32_f16 v[158:161], v[210:213], v[206:209], v[158:161]
	global_load_dwordx4 v[52:55], v[112:113], off offset:1792
	v_mfma_f32_16x16x32_f16 v[166:169], v[202:205], v[220:223], v[166:169]
	global_load_dwordx4 v[56:59], v[114:115], off offset:1792
	v_mfma_f32_16x16x32_f16 v[68:71], v[202:205], v[228:231], v[68:71]
	ds_read_b128 v[202:205], v136 offset:32768
	v_mfma_f32_16x16x32_f16 v[190:193], v[210:213], v[220:223], v[190:193]
	global_load_dwordx4 v[36:39], v[116:117], off offset:1792
	v_mfma_f32_16x16x32_f16 v[76:79], v[210:213], v[228:231], v[76:79]
	ds_read_b128 v[210:213], v136 offset:34816
	v_mfma_f32_16x16x32_f16 v[154:157], v[224:227], v[198:201], v[154:157]
	global_load_dwordx4 v[40:43], v[118:119], off offset:1792
	v_mfma_f32_16x16x32_f16 v[162:165], v[224:227], v[206:209], v[162:165]
	global_load_dwordx4 v[44:47], v[120:121], off offset:1792
	v_mfma_f32_16x16x32_f16 v[64:67], v[232:235], v[198:201], v[64:67]
	ds_read_b128 v[198:201], v133
	v_mfma_f32_16x16x32_f16 v[72:75], v[232:235], v[206:209], v[72:75]
	ds_read_b128 v[206:209], v133 offset:2048
	v_mfma_f32_16x16x32_f16 v[194:197], v[224:227], v[220:223], v[194:197]
	global_load_dwordx4 v[32:35], v[122:123], off offset:1792
	v_mfma_f32_16x16x32_f16 v[84:87], v[224:227], v[228:231], v[84:87]
	ds_read_b128 v[224:227], v136 offset:36864
	v_mfma_f32_16x16x32_f16 v[80:83], v[232:235], v[220:223], v[80:83]
	ds_read_b128 v[220:223], v133 offset:4096
	v_mfma_f32_16x16x32_f16 v[88:91], v[232:235], v[228:231], v[88:91]
	ds_read_b128 v[228:231], v133 offset:6144
	s_waitcnt lgkmcnt(4)
	v_mfma_f32_16x16x32_f16 v[138:141], v[202:205], v[198:201], v[138:141]
	ds_read_b128 v[232:235], v136 offset:38912
	s_waitcnt lgkmcnt(4)
	v_mfma_f32_16x16x32_f16 v[92:95], v[202:205], v[206:209], v[92:95]
	v_lshl_add_u64 v[20:21], v[108:109], 0, v[6:7]
	s_mov_b32 m0, s61
	s_nop 0
	global_load_lds_dwordx4 v[20:21], off
	v_mfma_f32_16x16x32_f16 v[142:145], v[210:213], v[198:201], v[142:145]
	v_lshl_add_u64 v[24:25], v[110:111], 0, v[6:7]
	s_mov_b32 m0, s69
	s_nop 0
	global_load_lds_dwordx4 v[24:25], off
	v_mfma_f32_16x16x32_f16 v[158:161], v[210:213], v[206:209], v[158:161]
	v_lshl_add_u64 v[28:29], v[112:113], 0, v[6:7]
	s_mov_b32 m0, s73
	s_nop 0
	global_load_lds_dwordx4 v[28:29], off
	s_waitcnt lgkmcnt(2)
	v_mfma_f32_16x16x32_f16 v[166:169], v[202:205], v[220:223], v[166:169]
	v_lshl_add_u64 v[8:9], v[114:115], 0, v[6:7]
	s_mov_b32 m0, s65
	s_nop 0
	global_load_lds_dwordx4 v[8:9], off
	s_waitcnt lgkmcnt(1)
; #define GL_LOAD(s_, kt_) if (VAR != 1) { a##s_##0 = GL_A(0, kt_); a##s_##1 = GL_A(1, kt_); a##s_##2 = GL_A(2, kt_); a##s_##3 = GL_A(3, kt_); b##s_##0 = GL_B(0, kt_); b##s_##1 = GL_B(1, kt_); b##s_##2 = GL_B(2, kt_); b##s_##3 = GL_B(3, kt_); }
; #define LDS_STORE(s_, buf_) if (VAR != 2) { LDS_ST1(sA, 0, buf_, a##s_##0) LDS_ST1(sA, 1, buf_, a##s_##1) LDS_ST1(sA, 2, buf_, a##s_##2) LDS_ST1(sA, 3, buf_, a##s_##3) LDS_ST1(sB, 0, buf_, b##s_##0) LDS_ST1(sB, 1, buf_, b##s_##1) LDS_ST1(sB, 2, buf_, b##s_##2) LDS_ST1(sB, 3, buf_, b##s_##3) }
;     ...
;   GL_LOAD(0, 0)
;   GL_LOAD(1, 1)
;   LDS_STORE(0, 0)
;   if (VAR != 4) __syncthreads();
; #pragma unroll
;   for (int kt = 0; kt < nk; kt += 2) {
;     if (kt + 2 < nk) { GL_LOAD(0, kt + 2) }
;     MMA_TILE(0)
;     LDS_STORE(1, 1)
;     if (VAR != 4) __syncthreads();
;     if (kt + 3 < nk) { GL_LOAD(1, kt + 3) }
;     MMA_TILE(1)
;     if (kt + 2 < nk) { LDS_STORE(0, 0) }
;     if (VAR != 4) __syncthreads();
	v_mfma_f32_16x16x32_f16 v[68:71], v[202:205], v[228:231], v[68:71]
	ds_read_b128 v[202:205], v135 offset:32768
	v_mfma_f32_16x16x32_f16 v[190:193], v[210:213], v[220:223], v[190:193]
	v_lshl_add_u64 v[12:13], v[116:117], 0, v[6:7]
	s_mov_b32 m0, s63
	s_nop 0
	global_load_lds_dwordx4 v[12:13], off
	v_mfma_f32_16x16x32_f16 v[76:79], v[210:213], v[228:231], v[76:79]
	ds_read_b128 v[210:213], v135 offset:34816
	v_mfma_f32_16x16x32_f16 v[154:157], v[224:227], v[198:201], v[154:157]
	v_lshl_add_u64 v[16:17], v[118:119], 0, v[6:7]
	s_mov_b32 m0, s71
	s_nop 0
	global_load_lds_dwordx4 v[16:17], off
	v_mfma_f32_16x16x32_f16 v[162:165], v[224:227], v[206:209], v[162:165]
	v_lshl_add_u64 v[0:1], v[120:121], 0, v[6:7]
	s_mov_b32 m0, s75
	s_nop 0
	global_load_lds_dwordx4 v[0:1], off
	s_waitcnt lgkmcnt(2)
	v_mfma_f32_16x16x32_f16 v[64:67], v[232:235], v[198:201], v[64:67]
	ds_read_b128 v[198:201], v134
	v_mfma_f32_16x16x32_f16 v[72:75], v[232:235], v[206:209], v[72:75]
	ds_read_b128 v[206:209], v134 offset:2048
	v_mfma_f32_16x16x32_f16 v[194:197], v[224:227], v[220:223], v[194:197]
	v_lshl_add_u64 v[4:5], v[122:123], 0, v[6:7]
	s_mov_b32 m0, s67
	s_nop 0
	global_load_lds_dwordx4 v[4:5], off
	v_mfma_f32_16x16x32_f16 v[84:87], v[224:227], v[228:231], v[84:87]
	ds_read_b128 v[224:227], v135 offset:36864
	v_mfma_f32_16x16x32_f16 v[80:83], v[232:235], v[220:223], v[80:83]
	ds_read_b128 v[220:223], v134 offset:4096
	v_mfma_f32_16x16x32_f16 v[88:91], v[232:235], v[228:231], v[88:91]
	ds_read_b128 v[228:231], v134 offset:6144
	ds_read_b128 v[232:235], v135 offset:38912
	s_waitcnt vmcnt(0) lgkmcnt(0)
	s_barrier
	v_mfma_f32_16x16x32_f16 v[138:141], v[202:205], v[198:201], v[138:141]
	global_load_dwordx4 v[28:31], v[108:109], off offset:1920
	v_mfma_f32_16x16x32_f16 v[92:95], v[202:205], v[206:209], v[92:95]
	global_load_dwordx4 v[16:19], v[110:111], off offset:1920
	v_mfma_f32_16x16x32_f16 v[142:145], v[210:213], v[198:201], v[142:145]
	ds_read_b128 v[108:111], v133 offset:16384
	v_mfma_f32_16x16x32_f16 v[158:161], v[210:213], v[206:209], v[158:161]
	global_load_dwordx4 v[20:23], v[112:113], off offset:1920
	v_mfma_f32_16x16x32_f16 v[166:169], v[202:205], v[220:223], v[166:169]
	global_load_dwordx4 v[24:27], v[114:115], off offset:1920
	v_mfma_f32_16x16x32_f16 v[68:71], v[202:205], v[228:231], v[68:71]
	ds_read_b128 v[112:115], v136 offset:49152
	v_mfma_f32_16x16x32_f16 v[190:193], v[210:213], v[220:223], v[190:193]
	ds_read_b128 v[202:205], v136 offset:53248
	v_mfma_f32_16x16x32_f16 v[76:79], v[210:213], v[228:231], v[76:79]
	ds_read_b128 v[210:213], v136 offset:55296
	v_mfma_f32_16x16x32_f16 v[154:157], v[224:227], v[198:201], v[154:157]
	global_load_dwordx4 v[4:7], v[116:117], off offset:1920
	v_mfma_f32_16x16x32_f16 v[162:165], v[224:227], v[206:209], v[162:165]
	global_load_dwordx4 v[8:11], v[118:119], off offset:1920
	v_mfma_f32_16x16x32_f16 v[64:67], v[232:235], v[198:201], v[64:67]
	ds_read_b128 v[116:119], v133 offset:18432
	v_mfma_f32_16x16x32_f16 v[72:75], v[232:235], v[206:209], v[72:75]
	ds_read_b128 v[198:201], v133 offset:20480
	v_mfma_f32_16x16x32_f16 v[194:197], v[224:227], v[220:223], v[194:197]
	ds_read_b128 v[206:209], v133 offset:22528
	v_mfma_f32_16x16x32_f16 v[84:87], v[224:227], v[228:231], v[84:87]
	global_load_dwordx4 v[12:15], v[120:121], off offset:1920
	v_mfma_f32_16x16x32_f16 v[80:83], v[232:235], v[220:223], v[80:83]
	global_load_dwordx4 v[0:3], v[122:123], off offset:1920
	v_mfma_f32_16x16x32_f16 v[88:91], v[232:235], v[228:231], v[88:91]
	ds_read_b128 v[120:123], v136 offset:51200
	s_waitcnt lgkmcnt(6)
	v_mfma_f32_16x16x32_f16 v[138:141], v[112:115], v[108:111], v[138:141]
	ds_write_b128 v101, v[60:63]
	s_waitcnt lgkmcnt(4)
	v_mfma_f32_16x16x32_f16 v[92:95], v[112:115], v[116:119], v[92:95]
	ds_write_b128 v131, v[48:51]
	s_waitcnt lgkmcnt(2)
	v_mfma_f32_16x16x32_f16 v[142:145], v[120:123], v[108:111], v[142:145]
	ds_write_b128 v132, v[52:55]
	v_mfma_f32_16x16x32_f16 v[154:157], v[202:205], v[108:111], v[154:157]
	v_mfma_f32_16x16x32_f16 v[64:67], v[210:213], v[108:111], v[64:67]
	v_mfma_f32_16x16x32_f16 v[108:111], v[120:123], v[116:119], v[158:161]
	ds_write_b128 v130, v[56:59]
	v_mfma_f32_16x16x32_f16 v[158:161], v[202:205], v[116:119], v[162:165]
	v_mfma_f32_16x16x32_f16 v[72:75], v[210:213], v[116:119], v[72:75]
	v_mfma_f32_16x16x32_f16 v[116:119], v[112:115], v[198:201], v[166:169]
	ds_write_b128 v101, v[36:39] offset:32768
	ds_write_b128 v131, v[40:43] offset:32768
	v_mfma_f32_16x16x32_f16 v[68:71], v[112:115], v[206:209], v[68:71]
	ds_read_b128 v[112:115], v134 offset:16384
	ds_write_b128 v132, v[44:47] offset:32768
	v_mfma_f32_16x16x32_f16 v[162:165], v[120:123], v[198:201], v[190:193]
	s_nop 2
	ds_read_b128 v[190:193], v134 offset:18432
	v_mfma_f32_16x16x32_f16 v[76:79], v[120:123], v[206:209], v[76:79]
	ds_read_b128 v[120:123], v135 offset:49152
	ds_write_b128 v130, v[32:35] offset:32768
	v_mfma_f32_16x16x32_f16 v[166:169], v[202:205], v[198:201], v[194:197]
	s_nop 2
	ds_read_b128 v[194:197], v135 offset:51200
	v_mfma_f32_16x16x32_f16 v[84:87], v[202:205], v[206:209], v[84:87]
	ds_read_b128 v[202:205], v135 offset:53248
	v_mfma_f32_16x16x32_f16 v[80:83], v[210:213], v[198:201], v[80:83]
	ds_read_b128 v[198:201], v134 offset:20480
	v_mfma_f32_16x16x32_f16 v[88:91], v[210:213], v[206:209], v[88:91]
	ds_read_b128 v[206:209], v134 offset:22528
	s_waitcnt lgkmcnt(5)
	v_mfma_f32_16x16x32_f16 v[138:141], v[120:123], v[112:115], v[138:141]
	ds_read_b128 v[210:213], v135 offset:55296
	s_waitcnt lgkmcnt(0)
	s_barrier
; #define GL_LOAD(s_, kt_) if (VAR != 1) { a##s_##0 = GL_A(0, kt_); a##s_##1 = GL_A(1, kt_); a##s_##2 = GL_A(2, kt_); a##s_##3 = GL_A(3, kt_); b##s_##0 = GL_B(0, kt_); b##s_##1 = GL_B(1, kt_); b##s_##2 = GL_B(2, kt_); b##s_##3 = GL_B(3, kt_); }
; #define LDS_STORE(s_, buf_) if (VAR != 2) { LDS_ST1(sA, 0, buf_, a##s_##0) LDS_ST1(sA, 1, buf_, a##s_##1) LDS_ST1(sA, 2, buf_, a##s_##2) LDS_ST1(sA, 3, buf_, a##s_##3) LDS_ST1(sB, 0, buf_, b##s_##0) LDS_ST1(sB, 1, buf_, b##s_##1) LDS_ST1(sB, 2, buf_, b##s_##2) LDS_ST1(sB, 3, buf_, b##s_##3) }
;     ...
;   GL_LOAD(0, 0)
;   GL_LOAD(1, 1)
;   LDS_STORE(0, 0)
;   if (VAR != 4) __syncthreads();
; #pragma unroll
;   for (int kt = 0; kt < nk; kt += 2) {
;     if (kt + 2 < nk) { GL_LOAD(0, kt + 2) }
;     MMA_TILE(0)
;     LDS_STORE(1, 1)
;     if (VAR != 4) __syncthreads();
;     if (kt + 3 < nk) { GL_LOAD(1, kt + 3) }
;     MMA_TILE(1)
;     if (kt + 2 < nk) { LDS_STORE(0, 0) }
;     if (VAR != 4) __syncthreads();
	v_mfma_f32_16x16x32_f16 v[142:145], v[194:197], v[112:115], v[142:145]
	ds_read_b128 v[32:35], v133
	v_mfma_f32_16x16x32_f16 v[108:111], v[194:197], v[190:193], v[108:111]
	ds_read_b128 v[36:39], v136 offset:32768
	v_mfma_f32_16x16x32_f16 v[154:157], v[202:205], v[112:115], v[154:157]
	ds_read_b128 v[40:43], v133 offset:2048
	v_mfma_f32_16x16x32_f16 v[64:67], v[210:213], v[112:115], v[64:67]
	v_mfma_f32_16x16x32_f16 v[112:115], v[202:205], v[190:193], v[158:161]
	ds_read_b128 v[44:47], v136 offset:34816
	v_mfma_f32_16x16x32_f16 v[158:161], v[194:197], v[198:201], v[162:165]
	ds_read_b128 v[48:51], v133 offset:4096
	v_mfma_f32_16x16x32_f16 v[76:79], v[194:197], v[206:209], v[76:79]
	ds_read_b128 v[52:55], v136 offset:36864
	v_mfma_f32_16x16x32_f16 v[162:165], v[202:205], v[198:201], v[166:169]
	ds_read_b128 v[56:59], v133 offset:6144
	v_mfma_f32_16x16x32_f16 v[84:87], v[202:205], v[206:209], v[84:87]
	ds_read_b128 v[60:63], v136 offset:38912
	s_waitcnt vmcnt(7)
	ds_write_b128 v101, v[28:31] offset:16384
	v_mfma_f32_16x16x32_f16 v[72:75], v[210:213], v[190:193], v[72:75]
	s_waitcnt vmcnt(6)
	ds_write_b128 v131, v[16:19] offset:16384
	v_mfma_f32_16x16x32_f16 v[92:95], v[120:123], v[190:193], v[92:95]
	s_waitcnt vmcnt(5)
	ds_write_b128 v132, v[20:23] offset:16384
	v_mfma_f32_16x16x32_f16 v[80:83], v[210:213], v[198:201], v[80:83]
	s_waitcnt vmcnt(4)
	ds_write_b128 v130, v[24:27] offset:16384
	v_mfma_f32_16x16x32_f16 v[88:91], v[210:213], v[206:209], v[88:91]
	s_waitcnt vmcnt(3)
	ds_write_b128 v101, v[4:7] offset:49152
	v_mfma_f32_16x16x32_f16 v[116:119], v[120:123], v[198:201], v[116:119]
	s_waitcnt vmcnt(2)
	ds_write_b128 v131, v[8:11] offset:49152
	v_mfma_f32_16x16x32_f16 v[68:71], v[120:123], v[206:209], v[68:71]
	s_waitcnt vmcnt(1)
	ds_write_b128 v132, v[12:15] offset:49152
	s_waitcnt lgkmcnt(13)
	v_mfma_f32_16x16x32_f16 v[120:123], v[36:39], v[32:35], v[138:141]
	s_waitcnt vmcnt(0)
	ds_write_b128 v130, v[0:3] offset:49152
	s_waitcnt lgkmcnt(12)
	v_mfma_f32_16x16x32_f16 v[138:141], v[44:47], v[32:35], v[142:145]
	s_waitcnt lgkmcnt(10)
	v_mfma_f32_16x16x32_f16 v[142:145], v[52:55], v[32:35], v[154:157]
	s_waitcnt lgkmcnt(8)
	v_mfma_f32_16x16x32_f16 v[32:35], v[60:63], v[32:35], v[64:67]
	v_mfma_f32_16x16x32_f16 v[64:67], v[36:39], v[40:43], v[92:95]
	ds_read_b128 v[154:157], v134 offset:6144
	v_mfma_f32_16x16x32_f16 v[92:95], v[44:47], v[40:43], v[108:111]
	v_mfma_f32_16x16x32_f16 v[108:111], v[52:55], v[40:43], v[112:115]
	v_mfma_f32_16x16x32_f16 v[40:43], v[60:63], v[40:43], v[72:75]
	v_mfma_f32_16x16x32_f16 v[72:75], v[36:39], v[48:51], v[116:119]
	v_mfma_f32_16x16x32_f16 v[36:39], v[36:39], v[56:59], v[68:71]
	s_nop 2
	ds_read_b128 v[68:71], v135 offset:32768
	v_mfma_f32_16x16x32_f16 v[112:115], v[44:47], v[48:51], v[158:161]
	s_nop 2
	ds_read_b128 v[158:161], v135 offset:38912
	v_mfma_f32_16x16x32_f16 v[44:47], v[44:47], v[56:59], v[76:79]
	s_nop 2
	ds_read_b128 v[76:79], v134 offset:2048
	v_mfma_f32_16x16x32_f16 v[116:119], v[52:55], v[48:51], v[162:165]
	v_mfma_f32_16x16x32_f16 v[52:55], v[52:55], v[56:59], v[84:87]
	s_nop 2
	ds_read_b128 v[84:87], v134 offset:4096
	v_mfma_f32_16x16x32_f16 v[48:51], v[60:63], v[48:51], v[80:83]
	s_nop 2
	ds_read_b128 v[80:83], v135 offset:34816
	v_mfma_f32_16x16x32_f16 v[56:59], v[60:63], v[56:59], v[88:91]
	ds_read_b128 v[60:63], v134
	s_waitcnt lgkmcnt(0)
	v_mfma_f32_16x16x32_f16 v[120:123], v[68:71], v[60:63], v[120:123]
	ds_read_b128 v[88:91], v135 offset:36864
	s_waitcnt lgkmcnt(0)
	s_barrier
	v_mfma_f32_16x16x32_f16 v[138:141], v[80:83], v[60:63], v[138:141]
	ds_read_b128 v[0:3], v133 offset:16384
	v_mfma_f32_16x16x32_f16 v[142:145], v[88:91], v[60:63], v[142:145]
	v_mfma_f32_16x16x32_f16 v[32:35], v[158:161], v[60:63], v[32:35]
	v_mfma_f32_16x16x32_f16 v[60:63], v[68:71], v[76:79], v[64:67]
	v_mfma_f32_16x16x32_f16 v[64:67], v[80:83], v[76:79], v[92:95]
	ds_read_b128 v[4:7], v136 offset:49152
	ds_read_b128 v[8:11], v133 offset:18432
	v_mfma_f32_16x16x32_f16 v[92:95], v[88:91], v[76:79], v[108:111]
	ds_read_b128 v[12:15], v136 offset:51200
	v_mfma_f32_16x16x32_f16 v[40:43], v[158:161], v[76:79], v[40:43]
	v_mfma_f32_16x16x32_f16 v[76:79], v[80:83], v[84:87], v[112:115]
	ds_read_b128 v[16:19], v133 offset:20480
	v_mfma_f32_16x16x32_f16 v[44:47], v[80:83], v[154:157], v[44:47]
	ds_read_b128 v[20:23], v136 offset:53248
	v_mfma_f32_16x16x32_f16 v[108:111], v[88:91], v[84:87], v[116:119]
	ds_read_b128 v[24:27], v133 offset:22528
	v_mfma_f32_16x16x32_f16 v[52:55], v[88:91], v[154:157], v[52:55]
	ds_read_b128 v[28:31], v136 offset:55296
	ds_read_b128 v[112:115], v135 offset:53248
	ds_read_b128 v[116:119], v134 offset:22528
	v_ashrrev_i32_e32 v101, 31, v100
	v_mfma_f32_16x16x32_f16 v[48:51], v[158:161], v[84:87], v[48:51]
	v_mfma_f32_16x16x32_f16 v[56:59], v[158:161], v[154:157], v[56:59]
	v_mfma_f32_16x16x32_f16 v[72:75], v[68:71], v[84:87], v[72:75]
	v_mfma_f32_16x16x32_f16 v[36:39], v[68:71], v[154:157], v[36:39]
	s_waitcnt lgkmcnt(8)
	v_mfma_f32_16x16x32_f16 v[68:71], v[4:7], v[0:3], v[120:123]
	s_nop 2
	ds_read_b128 v[120:123], v135 offset:55296
	s_waitcnt lgkmcnt(7)
	v_mfma_f32_16x16x32_f16 v[80:83], v[12:15], v[0:3], v[138:141]
	s_waitcnt lgkmcnt(5)
	v_mfma_f32_16x16x32_f16 v[84:87], v[20:23], v[0:3], v[142:145]
	s_waitcnt lgkmcnt(3)
	v_mfma_f32_16x16x32_f16 v[0:3], v[28:31], v[0:3], v[32:35]
	v_mfma_f32_16x16x32_f16 v[32:35], v[4:7], v[8:11], v[60:63]
	v_mfma_f32_16x16x32_f16 v[60:63], v[12:15], v[8:11], v[64:67]
	v_mfma_f32_16x16x32_f16 v[72:75], v[4:7], v[16:19], v[72:75]
	v_mfma_f32_16x16x32_f16 v[76:79], v[12:15], v[16:19], v[76:79]
	v_mfma_f32_16x16x32_f16 v[44:47], v[12:15], v[24:27], v[44:47]
	ds_read_b128 v[12:15], v134 offset:16384
	v_mfma_f32_16x16x32_f16 v[64:67], v[20:23], v[8:11], v[92:95]
	s_nop 2
	ds_read_b128 v[92:95], v135 offset:51200
	v_mfma_f32_16x16x32_f16 v[88:91], v[20:23], v[16:19], v[108:111]
	s_nop 2
	ds_read_b128 v[108:111], v134 offset:20480
	v_mfma_f32_16x16x32_f16 v[16:19], v[28:31], v[16:19], v[48:51]
	v_mfma_f32_16x16x32_f16 v[48:51], v[20:23], v[24:27], v[52:55]
	ds_read_b128 v[20:23], v134 offset:18432
	v_mfma_f32_16x16x32_f16 v[52:55], v[28:31], v[24:27], v[56:59]
	s_nop 2
	ds_read_b128 v[56:59], v135 offset:49152
	s_waitcnt lgkmcnt(0)
	s_barrier
; DI unsigned pack2(float lo, float hi) { f2_t v = {lo, hi}; h2_t b = __builtin_convertvector(v, h2_t); return __builtin_bit_cast(unsigned, b); }
; template <int VAR> DI void phase_up(const Params& P, int l, char* smem) {
;     ...
; #pragma unroll
;     for (int mt = 0; mt < 4; ++mt) {
;       const int row = row0 + mt * 16 + lr;
; #pragma unroll
;       for (int nt = 0; nt < 4; ++nt) {
;         float v[4];
; #pragma unroll
;         for (int j = 0; j < 4; ++j) { const float a = fmaxf(acc[mt][nt][j] * rs[mt], 0.f); v[j] = a * a; }
;         *(uint2*)(U + (size_t)row * DFF + col0 + nt * 16 + 4 * g) = make_uint2(pack2(v[0], v[1]), pack2(v[2], v[3]));
;       }
	s_setprio 0
	v_readlane_b32 s60, v255, 0
	v_readlane_b32 s61, v255, 1
	v_readlane_b32 s62, v255, 2
	v_readlane_b32 s63, v255, 3
	v_readlane_b32 s64, v255, 4
	v_readlane_b32 s65, v255, 5
	v_readlane_b32 s66, v255, 6
	v_readlane_b32 s67, v255, 7
	v_readlane_b32 s68, v255, 8
	v_readlane_b32 s69, v255, 9
	v_readlane_b32 s70, v255, 10
	v_readlane_b32 s71, v255, 11
	v_readlane_b32 s72, v255, 12
	v_readlane_b32 s73, v255, 13
	v_readlane_b32 s74, v255, 14
	v_readlane_b32 s75, v255, 15
	s_nop 4
	v_mfma_f32_16x16x32_f16 v[4:7], v[4:7], v[24:27], v[36:39]
	v_mfma_f32_16x16x32_f16 v[68:71], v[56:59], v[12:15], v[68:71]
	v_mfma_f32_16x16x32_f16 v[8:11], v[28:31], v[8:11], v[40:43]
	v_mfma_f32_16x16x32_f16 v[80:83], v[92:95], v[12:15], v[80:83]
	v_mfma_f32_16x16x32_f16 v[84:87], v[112:115], v[12:15], v[84:87]
	v_mfma_f32_16x16x32_f16 v[130:133], v[120:123], v[12:15], v[0:3]
	v_mfma_f32_16x16x32_f16 v[12:15], v[56:59], v[116:119], v[4:7]
	v_mfma_f32_16x16x32_f16 v[4:7], v[112:115], v[116:119], v[48:51]
	v_mfma_f32_16x16x32_f16 v[134:137], v[56:59], v[20:23], v[32:35]
	v_mfma_f32_16x16x32_f16 v[32:35], v[120:123], v[20:23], v[8:11]
	v_mfma_f32_16x16x32_f16 v[8:11], v[92:95], v[116:119], v[44:47]
	v_mfma_f32_16x16x32_f16 v[16:19], v[120:123], v[108:111], v[16:19]
	v_mfma_f32_16x16x32_f16 v[40:43], v[92:95], v[20:23], v[60:63]
	v_mfma_f32_16x16x32_f16 v[36:39], v[112:115], v[20:23], v[64:67]
	v_mfma_f32_16x16x32_f16 v[28:31], v[56:59], v[108:111], v[72:75]
	v_mfma_f32_16x16x32_f16 v[24:27], v[92:95], v[108:111], v[76:79]
	v_mfma_f32_16x16x32_f16 v[20:23], v[112:115], v[108:111], v[88:91]
	v_mfma_f32_16x16x32_f16 v[0:3], v[120:123], v[116:119], v[52:55]
	v_lshl_add_u64 v[44:45], v[100:101], 1, v[96:97]
	v_and_b32_e32 v46, 16, v148
	v_lshrrev_b32_e32 v47, 1, v46
	v_add_u32_e32 v46, v46, v47
	v_mov_b32_e32 v47, 0
	v_lshl_add_u64 v[44:45], v[46:47], 0, v[44:45]
	v_lshlrev_b64 v[46:47], 13, v[102:103]
	v_lshl_add_u64 v[46:47], v[44:45], 0, v[46:47]
	v_mul_f32_e32 v68, v128, v68
	v_mul_f32_e32 v69, v128, v69
	v_mul_f32_e32 v70, v128, v70
	v_mul_f32_e32 v71, v128, v71
	v_mul_f32_e32 v80, v128, v80
	v_mul_f32_e32 v81, v128, v81
	v_mul_f32_e32 v82, v128, v82
	v_mul_f32_e32 v83, v128, v83
	v_max_f32_e32 v68, 0, v68
	v_max_f32_e32 v69, 0, v69
	v_max_f32_e32 v70, 0, v70
	v_max_f32_e32 v71, 0, v71
	v_max_f32_e32 v80, 0, v80
	v_max_f32_e32 v81, 0, v81
	v_max_f32_e32 v82, 0, v82
	v_max_f32_e32 v83, 0, v83
	v_mul_f32_e32 v68, v68, v68
	v_mul_f32_e32 v69, v69, v69
	v_mul_f32_e32 v70, v70, v70
	v_mul_f32_e32 v71, v71, v71
	v_mul_f32_e32 v80, v80, v80
	v_mul_f32_e32 v81, v81, v81
	v_mul_f32_e32 v82, v82, v82
	v_mul_f32_e32 v83, v83, v83
	v_cvt_pk_f16_f32 v68, v68, v69
	v_cvt_pk_f16_f32 v69, v70, v71
	v_cvt_pk_f16_f32 v70, v80, v81
	v_cvt_pk_f16_f32 v71, v82, v83
	s_nop 1
	v_permlane16_swap_b32_e32 v68, v70
	v_permlane16_swap_b32_e32 v69, v71
	global_store_dwordx4 v[46:47], v[68:71], off
	v_mul_f32_e32 v84, v128, v84
	v_mul_f32_e32 v85, v128, v85
	v_mul_f32_e32 v86, v128, v86
	v_mul_f32_e32 v87, v128, v87
	v_mul_f32_e32 v130, v128, v130
	v_mul_f32_e32 v131, v128, v131
	v_mul_f32_e32 v132, v128, v132
	v_mul_f32_e32 v133, v128, v133
	v_max_f32_e32 v84, 0, v84
	v_max_f32_e32 v85, 0, v85
	v_max_f32_e32 v86, 0, v86
	v_max_f32_e32 v87, 0, v87
	v_max_f32_e32 v130, 0, v130
	v_max_f32_e32 v131, 0, v131
	v_max_f32_e32 v132, 0, v132
	v_max_f32_e32 v133, 0, v133
	v_mul_f32_e32 v84, v84, v84
	v_mul_f32_e32 v85, v85, v85
	v_mul_f32_e32 v86, v86, v86
	v_mul_f32_e32 v87, v87, v87
	v_mul_f32_e32 v130, v130, v130
	v_mul_f32_e32 v131, v131, v131
	v_mul_f32_e32 v132, v132, v132
	v_mul_f32_e32 v133, v133, v133
	v_cvt_pk_f16_f32 v84, v84, v85
	v_cvt_pk_f16_f32 v85, v86, v87
	v_cvt_pk_f16_f32 v86, v130, v131
	v_cvt_pk_f16_f32 v87, v132, v133
	s_nop 1
	v_permlane16_swap_b32_e32 v84, v86
	v_permlane16_swap_b32_e32 v85, v87
	global_store_dwordx4 v[46:47], v[84:87], off offset:64
	v_lshlrev_b64 v[46:47], 13, v[98:99]
	v_lshl_add_u64 v[46:47], v[44:45], 0, v[46:47]
	v_mul_f32_e32 v134, v126, v134
	v_mul_f32_e32 v135, v126, v135
	v_mul_f32_e32 v136, v126, v136
	v_mul_f32_e32 v137, v126, v137
	v_mul_f32_e32 v40, v126, v40
	v_mul_f32_e32 v41, v126, v41
	v_mul_f32_e32 v42, v126, v42
	v_mul_f32_e32 v43, v126, v43
	v_max_f32_e32 v134, 0, v134
	v_max_f32_e32 v135, 0, v135
	v_max_f32_e32 v136, 0, v136
	v_max_f32_e32 v137, 0, v137
	v_max_f32_e32 v40, 0, v40
	v_max_f32_e32 v41, 0, v41
	v_max_f32_e32 v42, 0, v42
	v_max_f32_e32 v43, 0, v43
	v_mul_f32_e32 v134, v134, v134
	v_mul_f32_e32 v135, v135, v135
	v_mul_f32_e32 v136, v136, v136
	v_mul_f32_e32 v137, v137, v137
	v_mul_f32_e32 v40, v40, v40
	v_mul_f32_e32 v41, v41, v41
	v_mul_f32_e32 v42, v42, v42
	v_mul_f32_e32 v43, v43, v43
	v_cvt_pk_f16_f32 v48, v134, v135
	v_cvt_pk_f16_f32 v49, v136, v137
	v_cvt_pk_f16_f32 v50, v40, v41
	v_cvt_pk_f16_f32 v51, v42, v43
	s_nop 1
	v_permlane16_swap_b32_e32 v48, v50
	v_permlane16_swap_b32_e32 v49, v51
; DI unsigned pack2(float lo, float hi) { f2_t v = {lo, hi}; h2_t b = __builtin_convertvector(v, h2_t); return __builtin_bit_cast(unsigned, b); }
; template <int VAR> DI void phase_up(const Params& P, int l, char* smem) {
;     ...
; #pragma unroll
;     for (int mt = 0; mt < 4; ++mt) {
;       const int row = row0 + mt * 16 + lr;
; #pragma unroll
;       for (int nt = 0; nt < 4; ++nt) {
;         float v[4];
; #pragma unroll
;         for (int j = 0; j < 4; ++j) { const float a = fmaxf(acc[mt][nt][j] * rs[mt], 0.f); v[j] = a * a; }
;         *(uint2*)(U + (size_t)row * DFF + col0 + nt * 16 + 4 * g) = make_uint2(pack2(v[0], v[1]), pack2(v[2], v[3]));
;       }
	global_store_dwordx4 v[46:47], v[48:51], off
	v_mul_f32_e32 v36, v126, v36
	v_mul_f32_e32 v37, v126, v37
	v_mul_f32_e32 v38, v126, v38
	v_mul_f32_e32 v39, v126, v39
	v_mul_f32_e32 v32, v126, v32
	v_mul_f32_e32 v33, v126, v33
	v_mul_f32_e32 v34, v126, v34
	v_mul_f32_e32 v35, v126, v35
	v_max_f32_e32 v36, 0, v36
	v_max_f32_e32 v37, 0, v37
	v_max_f32_e32 v38, 0, v38
	v_max_f32_e32 v39, 0, v39
	v_max_f32_e32 v32, 0, v32
	v_max_f32_e32 v33, 0, v33
	v_max_f32_e32 v34, 0, v34
	v_max_f32_e32 v35, 0, v35
	v_mul_f32_e32 v36, v36, v36
	v_mul_f32_e32 v37, v37, v37
	v_mul_f32_e32 v38, v38, v38
	v_mul_f32_e32 v39, v39, v39
	v_mul_f32_e32 v32, v32, v32
	v_mul_f32_e32 v33, v33, v33
	v_mul_f32_e32 v34, v34, v34
	v_mul_f32_e32 v35, v35, v35
	v_cvt_pk_f16_f32 v36, v36, v37
	v_cvt_pk_f16_f32 v37, v38, v39
	v_cvt_pk_f16_f32 v38, v32, v33
	v_cvt_pk_f16_f32 v39, v34, v35
	s_nop 1
	v_permlane16_swap_b32_e32 v36, v38
	v_permlane16_swap_b32_e32 v37, v39
	global_store_dwordx4 v[46:47], v[36:39], off offset:64
	v_lshlrev_b64 v[46:47], 13, v[106:107]
	v_lshl_add_u64 v[46:47], v[44:45], 0, v[46:47]
	v_mul_f32_e32 v28, v129, v28
	v_mul_f32_e32 v29, v129, v29
	v_mul_f32_e32 v30, v129, v30
	v_mul_f32_e32 v31, v129, v31
	v_mul_f32_e32 v24, v129, v24
	v_mul_f32_e32 v25, v129, v25
	v_mul_f32_e32 v26, v129, v26
	v_mul_f32_e32 v27, v129, v27
	v_max_f32_e32 v28, 0, v28
	v_max_f32_e32 v29, 0, v29
	v_max_f32_e32 v30, 0, v30
	v_max_f32_e32 v31, 0, v31
	v_max_f32_e32 v24, 0, v24
	v_max_f32_e32 v25, 0, v25
	v_max_f32_e32 v26, 0, v26
	v_max_f32_e32 v27, 0, v27
	v_mul_f32_e32 v28, v28, v28
	v_mul_f32_e32 v29, v29, v29
	v_mul_f32_e32 v30, v30, v30
	v_mul_f32_e32 v31, v31, v31
	v_mul_f32_e32 v24, v24, v24
	v_mul_f32_e32 v25, v25, v25
	v_mul_f32_e32 v26, v26, v26
	v_mul_f32_e32 v27, v27, v27
	v_cvt_pk_f16_f32 v28, v28, v29
	v_cvt_pk_f16_f32 v29, v30, v31
	v_cvt_pk_f16_f32 v30, v24, v25
	v_cvt_pk_f16_f32 v31, v26, v27
	s_nop 1
	v_permlane16_swap_b32_e32 v28, v30
	v_permlane16_swap_b32_e32 v29, v31
	global_store_dwordx4 v[46:47], v[28:31], off
	v_mul_f32_e32 v20, v129, v20
	v_mul_f32_e32 v21, v129, v21
	v_mul_f32_e32 v22, v129, v22
	v_mul_f32_e32 v23, v129, v23
	v_mul_f32_e32 v16, v129, v16
	v_mul_f32_e32 v17, v129, v17
	v_mul_f32_e32 v18, v129, v18
	v_mul_f32_e32 v19, v129, v19
	v_max_f32_e32 v20, 0, v20
	v_max_f32_e32 v21, 0, v21
	v_max_f32_e32 v22, 0, v22
	v_max_f32_e32 v23, 0, v23
	v_max_f32_e32 v16, 0, v16
	v_max_f32_e32 v17, 0, v17
	v_max_f32_e32 v18, 0, v18
	v_max_f32_e32 v19, 0, v19
	v_mul_f32_e32 v20, v20, v20
	v_mul_f32_e32 v21, v21, v21
	v_mul_f32_e32 v22, v22, v22
	v_mul_f32_e32 v23, v23, v23
	v_mul_f32_e32 v16, v16, v16
	v_mul_f32_e32 v17, v17, v17
	v_mul_f32_e32 v18, v18, v18
	v_mul_f32_e32 v19, v19, v19
	v_cvt_pk_f16_f32 v20, v20, v21
	v_cvt_pk_f16_f32 v21, v22, v23
	v_cvt_pk_f16_f32 v22, v16, v17
	v_cvt_pk_f16_f32 v23, v18, v19
	s_nop 1
	v_permlane16_swap_b32_e32 v20, v22
	v_permlane16_swap_b32_e32 v21, v23
	global_store_dwordx4 v[46:47], v[20:23], off offset:64
	v_lshlrev_b64 v[46:47], 13, v[104:105]
	v_lshl_add_u64 v[46:47], v[44:45], 0, v[46:47]
	v_mul_f32_e32 v12, v127, v12
	v_mul_f32_e32 v13, v127, v13
	v_mul_f32_e32 v14, v127, v14
	v_mul_f32_e32 v15, v127, v15
	v_mul_f32_e32 v8, v127, v8
	v_mul_f32_e32 v9, v127, v9
	v_mul_f32_e32 v10, v127, v10
	v_mul_f32_e32 v11, v127, v11
	v_max_f32_e32 v12, 0, v12
	v_max_f32_e32 v13, 0, v13
	v_max_f32_e32 v14, 0, v14
	v_max_f32_e32 v15, 0, v15
	v_max_f32_e32 v8, 0, v8
	v_max_f32_e32 v9, 0, v9
	v_max_f32_e32 v10, 0, v10
	v_max_f32_e32 v11, 0, v11
	v_mul_f32_e32 v12, v12, v12
	v_mul_f32_e32 v13, v13, v13
	v_mul_f32_e32 v14, v14, v14
	v_mul_f32_e32 v15, v15, v15
	v_mul_f32_e32 v8, v8, v8
	v_mul_f32_e32 v9, v9, v9
	v_mul_f32_e32 v10, v10, v10
	v_mul_f32_e32 v11, v11, v11
	v_cvt_pk_f16_f32 v12, v12, v13
	v_cvt_pk_f16_f32 v13, v14, v15
	v_cvt_pk_f16_f32 v14, v8, v9
	v_cvt_pk_f16_f32 v15, v10, v11
	s_nop 1
	v_permlane16_swap_b32_e32 v12, v14
	v_permlane16_swap_b32_e32 v13, v15
	global_store_dwordx4 v[46:47], v[12:15], off
	v_mul_f32_e32 v4, v127, v4
	v_mul_f32_e32 v5, v127, v5
	v_mul_f32_e32 v6, v127, v6
	v_mul_f32_e32 v7, v127, v7
	v_mul_f32_e32 v0, v127, v0
	v_mul_f32_e32 v1, v127, v1
	v_mul_f32_e32 v2, v127, v2
	v_mul_f32_e32 v3, v127, v3
	v_max_f32_e32 v4, 0, v4
	v_max_f32_e32 v5, 0, v5
	v_max_f32_e32 v6, 0, v6
	v_max_f32_e32 v7, 0, v7
	v_max_f32_e32 v0, 0, v0
	v_max_f32_e32 v1, 0, v1
	v_max_f32_e32 v2, 0, v2
	v_max_f32_e32 v3, 0, v3
	v_mul_f32_e32 v4, v4, v4
	v_mul_f32_e32 v5, v5, v5
	v_mul_f32_e32 v6, v6, v6
	v_mul_f32_e32 v7, v7, v7
	v_mul_f32_e32 v0, v0, v0
	v_mul_f32_e32 v1, v1, v1
	v_mul_f32_e32 v2, v2, v2
	v_mul_f32_e32 v3, v3, v3
	v_cvt_pk_f16_f32 v4, v4, v5
	v_cvt_pk_f16_f32 v5, v6, v7
	v_cvt_pk_f16_f32 v6, v0, v1
	v_cvt_pk_f16_f32 v7, v2, v3
	s_nop 1
	v_permlane16_swap_b32_e32 v4, v6
	v_permlane16_swap_b32_e32 v5, v7
	global_store_dwordx4 v[46:47], v[4:7], off offset:64
	s_branch .LBB0_1312
